# MFMA order within each 16-group: the two K-halves of every accumulator back to back (GIN, UP, GOUT, F1 loops)
# speedup vs baseline: 1.0040x; 1.0040x over previous
; #define PG8_STAGE(bufoff, gbase, voff) do { _Pragma("unroll") for (int _i = 0; _i < 2; ++_i) \
;         __builtin_amdgcn_global_load_lds((const unsigned*)((const char*)(gbase) + (voff)[_i]), (PG8_LAS unsigned*)(lds + (bufoff) + ldsw + _i * 8192), 16, 0, 0); } while (0)
; #define PG8_LDA(dst, b, h) do { _Pragma("unroll") for (int m = 0; m < 4; ++m) _Pragma("unroll") for (int k = 0; k < 2; ++k) dst[m][k] = *(const PG8_LAS bf16x8*)(lds + PG8_SA(b, h) + aoff + m * 2048 + k * 1024); } while (0)
; #define PG8_LDB(dst, b, h) do { _Pragma("unroll") for (int n = 0; n < 2; ++n) _Pragma("unroll") for (int k = 0; k < 2; ++k) dst[n][k] = *(const PG8_LAS bf16x8*)(lds + PG8_SB(b, h) + boff + n * 2048 + k * 1024); } while (0)
; #define PG8_MMA(ai, bj, At, Bt) do { __builtin_amdgcn_s_setprio(1); _Pragma("unroll") for (int m = 0; m < 4; ++m) _Pragma("unroll") for (int n = 0; n < 2; ++n) _Pragma("unroll") for (int k = 0; k < 2; ++k) \
;         acc[ai][bj][m][n] = __builtin_amdgcn_mfma_f32_16x16x32_bf16(Bt[n][k], At[m][k], acc[ai][bj][m][n], 0, 0, 0); __builtin_amdgcn_s_setprio(0); } while (0)
; #define PG8_WAIT_V(n) asm volatile("s_waitcnt vmcnt(" #n ")" ::: "memory")
; #define PG8_BAR __builtin_amdgcn_s_barrier()
; template <class Epi, class Sched, bool ALIGN_EPI = true, bool SP2 = true>
; __device__ __forceinline__ void gemm_phase(PG8_LAS unsigned char* lds, const Gemm g, const Sched& S, const Epi& E, const int tid) {
;     ...
;         for (int t = 0; t < nt; t += 2) {
;             const bool last = (t == nt - 2);
;             const char* a1 = cA + (size_t)(t + 1) * kstep;
;             const char* a2 = last ? nA : cA + (size_t)(t + 2) * kstep; const char* b2 = last ? nB : cB + (size_t)(t + 2) * kstep;
;             const char* a3 = a2 + kstep; const char* b3 = b2 + kstep;
;             if (last && has_next) S.a_ready(nxt);
;             if constexpr (SP2) {
;             PG8_LDB(B0, 0, 0); PG8_LDB(B1, 0, 1); PG8_SCHED; PG8_LDA(At, 0, 0); PG8_STAGE(PG8_SA(1, 1), a1 + hstepA, voffA);
;             PG8_WAIT_V(8); PG8_WAIT_L(0); PG8_BAR; PG8_MMA(0, 0, At, B0); PG8_MMA(0, 1, At, B1); PG8_BAR; PG8_SCHED;
;             PG8_LDA(At, 0, 1); PG8_STAGE(PG8_SB(0, 0), b2, voffB); PG8_STAGE(PG8_SB(0, 1), b2 + hstepB, voffB); PG8_STAGE(PG8_SA(0, 0), a2, voffA);
;             PG8_WAIT_V(8); PG8_WAIT_L(0); PG8_BAR; PG8_MMA(1, 0, At, B0); PG8_MMA(1, 1, At, B1); PG8_BAR; PG8_SCHED;
.LBB0_381:
	s_add_u32 s25, s62, 0xfff80080
	s_addc_u32 s26, s63, -1
	s_add_i32 s27, 0, 0x10000
	s_cmp_eq_u32 s24, 28
	s_cselect_b32 s69, s18, s26
	s_cselect_b32 s68, s19, s25
	s_cselect_b32 s67, s20, s23
	s_cselect_b32 s66, s21, s22
	s_add_i32 s25, 0, 0x14000
	v_add_u32_e32 v158, s27, v163
	v_add_u32_e32 v165, s25, v163
	ds_read_b128 v[146:149], v158
	ds_read_b128 v[150:153], v158 offset:1024
	ds_read_b128 v[154:157], v158 offset:2048
	ds_read_b128 v[158:161], v158 offset:3072
	ds_read_b128 v[166:169], v165
	ds_read_b128 v[170:173], v165 offset:1024
	ds_read_b128 v[174:177], v165 offset:2048
	ds_read_b128 v[178:181], v165 offset:3072
	s_add_i32 m0, s82, 0xc000
	ds_read_b128 v[182:185], v164
	ds_read_b128 v[186:189], v164 offset:1024
	ds_read_b128 v[190:193], v164 offset:2048
	ds_read_b128 v[194:197], v164 offset:3072
	ds_read_b128 v[206:209], v164 offset:4096
	ds_read_b128 v[210:213], v164 offset:5120
	ds_read_b128 v[222:225], v164 offset:6144
	ds_read_b128 v[226:229], v164 offset:7168
	global_load_lds_dwordx4 v142, s[62:63]
	s_add_i32 m0, s82, 0xe000
	s_nop 0
	global_load_lds_dwordx4 v144, s[62:63]
	s_waitcnt vmcnt(8)
	s_waitcnt lgkmcnt(0)
	s_barrier
	s_setprio 1
	s_waitcnt lgkmcnt(0)
	v_mfma_f32_16x16x32_bf16 v[126:129], v[146:149], v[182:185], v[126:129]
	v_mfma_f32_16x16x32_bf16 v[126:129], v[150:153], v[186:189], v[126:129]
	ds_read_b128 v[200:203], v164 offset:16384
	v_mfma_f32_16x16x32_bf16 v[122:125], v[154:157], v[182:185], v[122:125]
	v_mfma_f32_16x16x32_bf16 v[122:125], v[158:161], v[186:189], v[122:125]
	v_mfma_f32_16x16x32_bf16 v[110:113], v[146:149], v[190:193], v[110:113]
	v_mfma_f32_16x16x32_bf16 v[110:113], v[150:153], v[194:197], v[110:113]
	ds_read_b128 v[218:221], v164 offset:17408
	v_mfma_f32_16x16x32_bf16 v[106:109], v[154:157], v[190:193], v[106:109]
	v_mfma_f32_16x16x32_bf16 v[106:109], v[158:161], v[194:197], v[106:109]
	v_mfma_f32_16x16x32_bf16 v[92:95], v[146:149], v[206:209], v[92:95]
	v_mfma_f32_16x16x32_bf16 v[92:95], v[150:153], v[210:213], v[92:95]
	ds_read_b128 v[230:233], v164 offset:18432
	v_mfma_f32_16x16x32_bf16 v[88:91], v[154:157], v[206:209], v[88:91]
	v_mfma_f32_16x16x32_bf16 v[88:91], v[158:161], v[210:213], v[88:91]
	v_mfma_f32_16x16x32_bf16 v[76:79], v[146:149], v[222:225], v[76:79]
	v_mfma_f32_16x16x32_bf16 v[76:79], v[150:153], v[226:229], v[76:79]
	ds_read_b128 v[234:237], v164 offset:19456
	v_mfma_f32_16x16x32_bf16 v[72:75], v[154:157], v[222:225], v[72:75]
	v_mfma_f32_16x16x32_bf16 v[72:75], v[158:161], v[226:229], v[72:75]
	s_setprio 0
	s_setprio 1
	v_mfma_f32_16x16x32_bf16 v[118:121], v[166:169], v[182:185], v[118:121]
	v_mfma_f32_16x16x32_bf16 v[118:121], v[170:173], v[186:189], v[118:121]
	ds_read_b128 v[238:241], v164 offset:20480
	v_mfma_f32_16x16x32_bf16 v[114:117], v[174:177], v[182:185], v[114:117]
	v_mfma_f32_16x16x32_bf16 v[114:117], v[178:181], v[186:189], v[114:117]
	v_mfma_f32_16x16x32_bf16 v[102:105], v[166:169], v[190:193], v[102:105]
	v_mfma_f32_16x16x32_bf16 v[102:105], v[170:173], v[194:197], v[102:105]
	ds_read_b128 v[242:245], v164 offset:21504
	v_mfma_f32_16x16x32_bf16 v[98:101], v[174:177], v[190:193], v[98:101]
	v_mfma_f32_16x16x32_bf16 v[98:101], v[178:181], v[194:197], v[98:101]
	v_mfma_f32_16x16x32_bf16 v[84:87], v[166:169], v[206:209], v[84:87]
	v_mfma_f32_16x16x32_bf16 v[84:87], v[170:173], v[210:213], v[84:87]
	ds_read_b128 v[246:249], v164 offset:22528
	v_mfma_f32_16x16x32_bf16 v[80:83], v[174:177], v[206:209], v[80:83]
	v_mfma_f32_16x16x32_bf16 v[80:83], v[178:181], v[210:213], v[80:83]
	v_mfma_f32_16x16x32_bf16 v[68:71], v[166:169], v[222:225], v[68:71]
	v_mfma_f32_16x16x32_bf16 v[68:71], v[170:173], v[226:229], v[68:71]
	v_mfma_f32_16x16x32_bf16 v[64:67], v[174:177], v[222:225], v[64:67]
	v_mfma_f32_16x16x32_bf16 v[64:67], v[178:181], v[226:229], v[64:67]
	s_setprio 0
	s_barrier
	s_add_i32 s26, s27, s73
	s_mov_b32 m0, s26
	ds_read_b128 v[226:229], v164 offset:23552
	global_load_lds_dwordx4 v132, s[66:67]
	s_add_i32 m0, s26, 0x2000
	s_add_u32 s26, s66, 0x80000
	s_addc_u32 s27, s67, 0
	s_add_i32 s25, s25, s73
	global_load_lds_dwordx4 v136, s[66:67]
	s_mov_b32 m0, s25
	s_nop 0
	global_load_lds_dwordx4 v132, s[26:27]
	s_add_i32 m0, s25, 0x2000
	s_nop 0
	global_load_lds_dwordx4 v136, s[26:27]
	s_mov_b32 m0, s82
	s_nop 0
	global_load_lds_dwordx4 v130, s[68:69]
	s_mov_b32 m0, s83
	s_nop 0
	global_load_lds_dwordx4 v134, s[68:69]
	s_waitcnt vmcnt(6)
	s_waitcnt lgkmcnt(0)
	s_barrier
	s_setprio 1
	s_waitcnt lgkmcnt(0)
	v_mfma_f32_16x16x32_bf16 v[60:63], v[146:149], v[200:203], v[60:63]
	v_mfma_f32_16x16x32_bf16 v[60:63], v[150:153], v[218:221], v[60:63]
	v_mfma_f32_16x16x32_bf16 v[56:59], v[154:157], v[200:203], v[56:59]
	v_mfma_f32_16x16x32_bf16 v[56:59], v[158:161], v[218:221], v[56:59]
	v_mfma_f32_16x16x32_bf16 v[44:47], v[146:149], v[230:233], v[44:47]
	v_mfma_f32_16x16x32_bf16 v[44:47], v[150:153], v[234:237], v[44:47]
	v_mfma_f32_16x16x32_bf16 v[40:43], v[154:157], v[230:233], v[40:43]
	v_mfma_f32_16x16x32_bf16 v[40:43], v[158:161], v[234:237], v[40:43]
	v_mfma_f32_16x16x32_bf16 v[28:31], v[146:149], v[238:241], v[28:31]
	v_mfma_f32_16x16x32_bf16 v[28:31], v[150:153], v[242:245], v[28:31]
	v_mfma_f32_16x16x32_bf16 v[24:27], v[154:157], v[238:241], v[24:27]
	v_mfma_f32_16x16x32_bf16 v[24:27], v[158:161], v[242:245], v[24:27]
	v_mfma_f32_16x16x32_bf16 v[12:15], v[146:149], v[246:249], v[12:15]
	v_mfma_f32_16x16x32_bf16 v[12:15], v[150:153], v[226:229], v[12:15]
	v_mfma_f32_16x16x32_bf16 v[8:11], v[154:157], v[246:249], v[8:11]
	v_mfma_f32_16x16x32_bf16 v[8:11], v[158:161], v[226:229], v[8:11]
	s_setprio 0
	s_setprio 1
	v_mfma_f32_16x16x32_bf16 v[52:55], v[166:169], v[200:203], v[52:55]
	v_mfma_f32_16x16x32_bf16 v[52:55], v[170:173], v[218:221], v[52:55]
	v_mfma_f32_16x16x32_bf16 v[48:51], v[174:177], v[200:203], v[48:51]
	v_mfma_f32_16x16x32_bf16 v[48:51], v[178:181], v[218:221], v[48:51]
	v_mfma_f32_16x16x32_bf16 v[36:39], v[166:169], v[230:233], v[36:39]
	v_mfma_f32_16x16x32_bf16 v[36:39], v[170:173], v[234:237], v[36:39]
	v_mfma_f32_16x16x32_bf16 v[32:35], v[174:177], v[230:233], v[32:35]
	v_mfma_f32_16x16x32_bf16 v[32:35], v[178:181], v[234:237], v[32:35]
	v_mfma_f32_16x16x32_bf16 v[20:23], v[166:169], v[238:241], v[20:23]
	v_mfma_f32_16x16x32_bf16 v[20:23], v[170:173], v[242:245], v[20:23]
	v_mfma_f32_16x16x32_bf16 v[16:19], v[174:177], v[238:241], v[16:19]
	v_mfma_f32_16x16x32_bf16 v[16:19], v[178:181], v[242:245], v[16:19]
	v_mfma_f32_16x16x32_bf16 v[4:7], v[166:169], v[246:249], v[4:7]
	v_mfma_f32_16x16x32_bf16 v[4:7], v[170:173], v[226:229], v[4:7]
	v_mfma_f32_16x16x32_bf16 v[0:3], v[174:177], v[246:249], v[0:3]
	v_mfma_f32_16x16x32_bf16 v[0:3], v[178:181], v[226:229], v[0:3]
	s_setprio 0
	s_barrier
; #define PG8_STAGE(bufoff, gbase, voff) do { _Pragma("unroll") for (int _i = 0; _i < 2; ++_i) \
;         __builtin_amdgcn_global_load_lds((const unsigned*)((const char*)(gbase) + (voff)[_i]), (PG8_LAS unsigned*)(lds + (bufoff) + ldsw + _i * 8192), 16, 0, 0); } while (0)
; #define PG8_LDA(dst, b, h) do { _Pragma("unroll") for (int m = 0; m < 4; ++m) _Pragma("unroll") for (int k = 0; k < 2; ++k) dst[m][k] = *(const PG8_LAS bf16x8*)(lds + PG8_SA(b, h) + aoff + m * 2048 + k * 1024); } while (0)
; #define PG8_LDB(dst, b, h) do { _Pragma("unroll") for (int n = 0; n < 2; ++n) _Pragma("unroll") for (int k = 0; k < 2; ++k) dst[n][k] = *(const PG8_LAS bf16x8*)(lds + PG8_SB(b, h) + boff + n * 2048 + k * 1024); } while (0)
; #define PG8_MMA(ai, bj, At, Bt) do { __builtin_amdgcn_s_setprio(1); _Pragma("unroll") for (int m = 0; m < 4; ++m) _Pragma("unroll") for (int n = 0; n < 2; ++n) _Pragma("unroll") for (int k = 0; k < 2; ++k) \
;         acc[ai][bj][m][n] = __builtin_amdgcn_mfma_f32_16x16x32_bf16(Bt[n][k], At[m][k], acc[ai][bj][m][n], 0, 0, 0); __builtin_amdgcn_s_setprio(0); } while (0)
; #define PG8_WAIT_V(n) asm volatile("s_waitcnt vmcnt(" #n ")" ::: "memory")
; #define PG8_WAIT_L(n) asm volatile("s_waitcnt lgkmcnt(" #n ")" ::: "memory")
; #define PG8_BAR __builtin_amdgcn_s_barrier()
; #define PG8_SCHED __builtin_amdgcn_sched_barrier(0)
; template <class Epi, class Sched, bool ALIGN_EPI = true, bool SP2 = true>
; __device__ __forceinline__ void gemm_phase(PG8_LAS unsigned char* lds, const Gemm g, const Sched& S, const Epi& E, const int tid) {
;     ...
;             PG8_LDB(B0, 1, 0); PG8_LDB(B1, 1, 1); PG8_SCHED; PG8_LDA(At, 1, 0); PG8_STAGE(PG8_SA(0, 1), a2 + hstepA, voffA);
;             PG8_WAIT_V(8); PG8_WAIT_L(0); PG8_BAR; PG8_MMA(0, 0, At, B0); PG8_MMA(0, 1, At, B1); PG8_BAR; PG8_SCHED;
;             PG8_LDA(At, 1, 1); PG8_STAGE(PG8_SB(1, 0), b3, voffB); PG8_STAGE(PG8_SB(1, 1), b3 + hstepB, voffB); PG8_STAGE(PG8_SA(1, 0), a3, voffA);
;             PG8_WAIT_V(8); PG8_WAIT_L(0); PG8_BAR; PG8_MMA(1, 0, At, B0); PG8_MMA(1, 1, At, B1); PG8_BAR; PG8_SCHED;
	s_add_i32 s25, 0, 0x18000
	s_add_i32 s28, 0, 0x1c000
	v_add_u32_e32 v158, s25, v163
	v_add_u32_e32 v165, s28, v163
	ds_read_b128 v[146:149], v158
	ds_read_b128 v[150:153], v158 offset:1024
	ds_read_b128 v[154:157], v158 offset:2048
	ds_read_b128 v[158:161], v158 offset:3072
	ds_read_b128 v[166:169], v165
	ds_read_b128 v[170:173], v165 offset:1024
	ds_read_b128 v[174:177], v165 offset:2048
	ds_read_b128 v[178:181], v165 offset:3072
	s_add_u32 s26, s68, 0x80000
	s_addc_u32 s27, s69, 0
	s_mov_b32 m0, s84
	ds_read_b128 v[182:185], v164 offset:32768
	ds_read_b128 v[186:189], v164 offset:33792
	ds_read_b128 v[190:193], v164 offset:34816
	ds_read_b128 v[194:197], v164 offset:35840
	ds_read_b128 v[206:209], v164 offset:36864
	ds_read_b128 v[210:213], v164 offset:37888
	ds_read_b128 v[222:225], v164 offset:38912
	ds_read_b128 v[226:229], v164 offset:39936
	global_load_lds_dwordx4 v130, s[26:27]
	s_mov_b32 m0, s85
	s_nop 0
	global_load_lds_dwordx4 v134, s[26:27]
	s_waitcnt vmcnt(8)
	s_waitcnt lgkmcnt(0)
	s_barrier
	s_setprio 1
	s_waitcnt lgkmcnt(0)
	v_mfma_f32_16x16x32_bf16 v[126:129], v[146:149], v[182:185], v[126:129]
	v_mfma_f32_16x16x32_bf16 v[126:129], v[150:153], v[186:189], v[126:129]
	ds_read_b128 v[200:203], v164 offset:49152
	v_mfma_f32_16x16x32_bf16 v[122:125], v[154:157], v[182:185], v[122:125]
	v_mfma_f32_16x16x32_bf16 v[122:125], v[158:161], v[186:189], v[122:125]
	v_mfma_f32_16x16x32_bf16 v[110:113], v[146:149], v[190:193], v[110:113]
	v_mfma_f32_16x16x32_bf16 v[110:113], v[150:153], v[194:197], v[110:113]
	ds_read_b128 v[218:221], v164 offset:50176
	v_mfma_f32_16x16x32_bf16 v[106:109], v[154:157], v[190:193], v[106:109]
	v_mfma_f32_16x16x32_bf16 v[106:109], v[158:161], v[194:197], v[106:109]
	v_mfma_f32_16x16x32_bf16 v[92:95], v[146:149], v[206:209], v[92:95]
	v_mfma_f32_16x16x32_bf16 v[92:95], v[150:153], v[210:213], v[92:95]
	ds_read_b128 v[230:233], v164 offset:51200
	v_mfma_f32_16x16x32_bf16 v[88:91], v[154:157], v[206:209], v[88:91]
	v_mfma_f32_16x16x32_bf16 v[88:91], v[158:161], v[210:213], v[88:91]
	v_mfma_f32_16x16x32_bf16 v[76:79], v[146:149], v[222:225], v[76:79]
	v_mfma_f32_16x16x32_bf16 v[76:79], v[150:153], v[226:229], v[76:79]
	ds_read_b128 v[234:237], v164 offset:52224
	v_mfma_f32_16x16x32_bf16 v[72:75], v[154:157], v[222:225], v[72:75]
	v_mfma_f32_16x16x32_bf16 v[72:75], v[158:161], v[226:229], v[72:75]
	s_setprio 0
	s_setprio 1
	v_mfma_f32_16x16x32_bf16 v[118:121], v[166:169], v[182:185], v[118:121]
	v_mfma_f32_16x16x32_bf16 v[118:121], v[170:173], v[186:189], v[118:121]
	ds_read_b128 v[238:241], v164 offset:53248
	v_mfma_f32_16x16x32_bf16 v[114:117], v[174:177], v[182:185], v[114:117]
	v_mfma_f32_16x16x32_bf16 v[114:117], v[178:181], v[186:189], v[114:117]
	v_mfma_f32_16x16x32_bf16 v[102:105], v[166:169], v[190:193], v[102:105]
	v_mfma_f32_16x16x32_bf16 v[102:105], v[170:173], v[194:197], v[102:105]
	ds_read_b128 v[242:245], v164 offset:54272
	v_mfma_f32_16x16x32_bf16 v[98:101], v[174:177], v[190:193], v[98:101]
	v_mfma_f32_16x16x32_bf16 v[98:101], v[178:181], v[194:197], v[98:101]
	v_mfma_f32_16x16x32_bf16 v[84:87], v[166:169], v[206:209], v[84:87]
	v_mfma_f32_16x16x32_bf16 v[84:87], v[170:173], v[210:213], v[84:87]
	ds_read_b128 v[246:249], v164 offset:55296
	v_mfma_f32_16x16x32_bf16 v[80:83], v[174:177], v[206:209], v[80:83]
	v_mfma_f32_16x16x32_bf16 v[80:83], v[178:181], v[210:213], v[80:83]
	v_mfma_f32_16x16x32_bf16 v[68:71], v[166:169], v[222:225], v[68:71]
	v_mfma_f32_16x16x32_bf16 v[68:71], v[170:173], v[226:229], v[68:71]
	v_mfma_f32_16x16x32_bf16 v[64:67], v[174:177], v[222:225], v[64:67]
	v_mfma_f32_16x16x32_bf16 v[64:67], v[178:181], v[226:229], v[64:67]
	s_setprio 0
	s_barrier
	s_add_i32 s25, s25, s73
	s_add_u32 s4, s66, 0x80
	s_addc_u32 s5, s67, 0
	s_mov_b32 m0, s25
	ds_read_b128 v[226:229], v164 offset:56320
	global_load_lds_dwordx4 v132, s[4:5]
	s_add_i32 m0, s25, 0x2000
	s_add_u32 s26, s66, 0x80080
	s_addc_u32 s27, s67, 0
	s_add_i32 s25, s28, s73
	global_load_lds_dwordx4 v136, s[4:5]
	s_mov_b32 m0, s25
	s_nop 0
	global_load_lds_dwordx4 v132, s[26:27]
	s_add_i32 m0, s25, 0x2000
	s_nop 0
	global_load_lds_dwordx4 v136, s[26:27]
	s_add_u32 s4, s68, 0x80
	s_addc_u32 s5, s69, 0
	s_mov_b32 m0, s88
	s_nop 0
	global_load_lds_dwordx4 v130, s[4:5]
	s_mov_b32 m0, s89
	s_nop 0
	global_load_lds_dwordx4 v134, s[4:5]
	s_waitcnt vmcnt(6)
	s_waitcnt lgkmcnt(0)
	s_barrier
	s_setprio 1
	s_waitcnt lgkmcnt(0)
	v_mfma_f32_16x16x32_bf16 v[60:63], v[146:149], v[200:203], v[60:63]
	v_mfma_f32_16x16x32_bf16 v[60:63], v[150:153], v[218:221], v[60:63]
	v_mfma_f32_16x16x32_bf16 v[56:59], v[154:157], v[200:203], v[56:59]
	v_mfma_f32_16x16x32_bf16 v[56:59], v[158:161], v[218:221], v[56:59]
	v_mfma_f32_16x16x32_bf16 v[44:47], v[146:149], v[230:233], v[44:47]
	v_mfma_f32_16x16x32_bf16 v[44:47], v[150:153], v[234:237], v[44:47]
	v_mfma_f32_16x16x32_bf16 v[40:43], v[154:157], v[230:233], v[40:43]
	v_mfma_f32_16x16x32_bf16 v[40:43], v[158:161], v[234:237], v[40:43]
	v_mfma_f32_16x16x32_bf16 v[28:31], v[146:149], v[238:241], v[28:31]
	v_mfma_f32_16x16x32_bf16 v[28:31], v[150:153], v[242:245], v[28:31]
	v_mfma_f32_16x16x32_bf16 v[24:27], v[154:157], v[238:241], v[24:27]
	v_mfma_f32_16x16x32_bf16 v[24:27], v[158:161], v[242:245], v[24:27]
	v_mfma_f32_16x16x32_bf16 v[12:15], v[146:149], v[246:249], v[12:15]
	v_mfma_f32_16x16x32_bf16 v[12:15], v[150:153], v[226:229], v[12:15]
	v_mfma_f32_16x16x32_bf16 v[8:11], v[154:157], v[246:249], v[8:11]
	v_mfma_f32_16x16x32_bf16 v[8:11], v[158:161], v[226:229], v[8:11]
	s_setprio 0
	s_setprio 1
	v_mfma_f32_16x16x32_bf16 v[52:55], v[166:169], v[200:203], v[52:55]
	v_mfma_f32_16x16x32_bf16 v[52:55], v[170:173], v[218:221], v[52:55]
	v_mfma_f32_16x16x32_bf16 v[48:51], v[174:177], v[200:203], v[48:51]
	v_mfma_f32_16x16x32_bf16 v[48:51], v[178:181], v[218:221], v[48:51]
	v_mfma_f32_16x16x32_bf16 v[36:39], v[166:169], v[230:233], v[36:39]
	v_mfma_f32_16x16x32_bf16 v[36:39], v[170:173], v[234:237], v[36:39]
	v_mfma_f32_16x16x32_bf16 v[32:35], v[174:177], v[230:233], v[32:35]
	v_mfma_f32_16x16x32_bf16 v[32:35], v[178:181], v[234:237], v[32:35]
	v_mfma_f32_16x16x32_bf16 v[20:23], v[166:169], v[238:241], v[20:23]
	v_mfma_f32_16x16x32_bf16 v[20:23], v[170:173], v[242:245], v[20:23]
	v_mfma_f32_16x16x32_bf16 v[16:19], v[174:177], v[238:241], v[16:19]
	v_mfma_f32_16x16x32_bf16 v[16:19], v[178:181], v[242:245], v[16:19]
	v_mfma_f32_16x16x32_bf16 v[4:7], v[166:169], v[246:249], v[4:7]
	v_mfma_f32_16x16x32_bf16 v[4:7], v[170:173], v[226:229], v[4:7]
	v_mfma_f32_16x16x32_bf16 v[0:3], v[174:177], v[246:249], v[0:3]
	v_mfma_f32_16x16x32_bf16 v[0:3], v[178:181], v[226:229], v[0:3]
	s_setprio 0
	s_barrier
	s_add_i32 s24, s24, 2
	s_add_u32 s62, s62, 0x100
	s_addc_u32 s63, s63, 0
	s_add_u32 s22, s22, 0x100
	s_addc_u32 s23, s23, 0
	s_cmp_gt_u32 s24, 29
	s_cbranch_scc0 .LBB0_381
	v_mov_b32_e32 v218, 0x2a00
	v_mov_b32_e32 v219, 0xf149f2ca
	v_mov_b32_e32 v220, 0xe00
	s_mov_b64 s[4:5], 0x80
	s_and_b64 vcc, exec, s[52:53]
	s_cbranch_vccz .LBB0_384
	s_barrier

; #define PG8_STAGE(bufoff, gbase, voff) do { _Pragma("unroll") for (int _i = 0; _i < 2; ++_i) \
;         __builtin_amdgcn_global_load_lds((const unsigned*)((const char*)(gbase) + (voff)[_i]), (PG8_LAS unsigned*)(lds + (bufoff) + ldsw + _i * 8192), 16, 0, 0); } while (0)
; #define PG8_LDA(dst, b, h) do { _Pragma("unroll") for (int m = 0; m < 4; ++m) _Pragma("unroll") for (int k = 0; k < 2; ++k) dst[m][k] = *(const PG8_LAS bf16x8*)(lds + PG8_SA(b, h) + aoff + m * 2048 + k * 1024); } while (0)
; #define PG8_LDB(dst, b, h) do { _Pragma("unroll") for (int n = 0; n < 2; ++n) _Pragma("unroll") for (int k = 0; k < 2; ++k) dst[n][k] = *(const PG8_LAS bf16x8*)(lds + PG8_SB(b, h) + boff + n * 2048 + k * 1024); } while (0)
; #define PG8_MMA(ai, bj, At, Bt) do { __builtin_amdgcn_s_setprio(1); _Pragma("unroll") for (int m = 0; m < 4; ++m) _Pragma("unroll") for (int n = 0; n < 2; ++n) _Pragma("unroll") for (int k = 0; k < 2; ++k) \
;         acc[ai][bj][m][n] = __builtin_amdgcn_mfma_f32_16x16x32_bf16(Bt[n][k], At[m][k], acc[ai][bj][m][n], 0, 0, 0); __builtin_amdgcn_s_setprio(0); } while (0)
; #define PG8_WAIT_V(n) asm volatile("s_waitcnt vmcnt(" #n ")" ::: "memory")
; #define PG8_BAR __builtin_amdgcn_s_barrier()
; template <class Epi, class Sched, bool ALIGN_EPI = true, bool SP2 = true>
; __device__ __forceinline__ void gemm_phase(PG8_LAS unsigned char* lds, const Gemm g, const Sched& S, const Epi& E, const int tid) {
;     ...
;         for (int t = 0; t < nt; t += 2) {
;             const bool last = (t == nt - 2);
;             const char* a1 = cA + (size_t)(t + 1) * kstep;
;             const char* a2 = last ? nA : cA + (size_t)(t + 2) * kstep; const char* b2 = last ? nB : cB + (size_t)(t + 2) * kstep;
;             const char* a3 = a2 + kstep; const char* b3 = b2 + kstep;
;             if (last && has_next) S.a_ready(nxt);
;             if constexpr (SP2) {
;             PG8_LDB(B0, 0, 0); PG8_LDB(B1, 0, 1); PG8_SCHED; PG8_LDA(At, 0, 0); PG8_STAGE(PG8_SA(1, 1), a1 + hstepA, voffA);
;             PG8_WAIT_V(8); PG8_WAIT_L(0); PG8_BAR; PG8_MMA(0, 0, At, B0); PG8_MMA(0, 1, At, B1); PG8_BAR; PG8_SCHED;
;             PG8_LDA(At, 0, 1); PG8_STAGE(PG8_SB(0, 0), b2, voffB); PG8_STAGE(PG8_SB(0, 1), b2 + hstepB, voffB); PG8_STAGE(PG8_SA(0, 0), a2, voffA);
;             PG8_WAIT_V(8); PG8_WAIT_L(0); PG8_BAR; PG8_MMA(1, 0, At, B0); PG8_MMA(1, 1, At, B1); PG8_BAR; PG8_SCHED;
.LBB0_700:
	s_add_i32 s29, s28, 2
	s_add_u32 s40, s42, 0x100
	s_addc_u32 s41, s43, 0
	s_add_i32 s48, 0, 0x10000
	s_cmp_eq_u32 s25, s28
	s_cselect_b32 s47, s71, s41
	s_cselect_b32 s46, s70, s40
	s_cselect_b32 s45, s73, s27
	s_cselect_b32 s44, s72, s26
	s_add_i32 s28, 0, 0x14000
	v_add_u32_e32 v162, s48, v152
	v_add_u32_e32 v178, s28, v152
	ds_read_b128 v[144:147], v162
	ds_read_b128 v[154:157], v162 offset:1024
	ds_read_b128 v[158:161], v162 offset:2048
	ds_read_b128 v[162:165], v162 offset:3072
	ds_read_b128 v[166:169], v178
	ds_read_b128 v[170:173], v178 offset:1024
	ds_read_b128 v[174:177], v178 offset:2048
	ds_read_b128 v[178:181], v178 offset:3072
	s_add_i32 m0, s89, 0xc000
	ds_read_b128 v[182:185], v153
	ds_read_b128 v[186:189], v153 offset:1024
	ds_read_b128 v[190:193], v153 offset:2048
	ds_read_b128 v[194:197], v153 offset:3072
	ds_read_b128 v[206:209], v153 offset:4096
	ds_read_b128 v[210:213], v153 offset:5120
	ds_read_b128 v[222:225], v153 offset:6144
	ds_read_b128 v[226:229], v153 offset:7168
	global_load_lds_dwordx4 v140, s[42:43]
	s_add_i32 m0, s89, 0xe000
	s_nop 0
	global_load_lds_dwordx4 v142, s[42:43]
	s_waitcnt vmcnt(8)
	s_waitcnt lgkmcnt(0)
	s_barrier
	s_setprio 1
	s_waitcnt lgkmcnt(0)
	v_mfma_f32_16x16x32_bf16 v[126:129], v[144:147], v[182:185], v[126:129]
	v_mfma_f32_16x16x32_bf16 v[126:129], v[154:157], v[186:189], v[126:129]
	v_mfma_f32_16x16x32_bf16 v[122:125], v[158:161], v[182:185], v[122:125]
	v_mfma_f32_16x16x32_bf16 v[122:125], v[162:165], v[186:189], v[122:125]
	v_mfma_f32_16x16x32_bf16 v[110:113], v[144:147], v[190:193], v[110:113]
	v_mfma_f32_16x16x32_bf16 v[110:113], v[154:157], v[194:197], v[110:113]
	v_mfma_f32_16x16x32_bf16 v[106:109], v[158:161], v[190:193], v[106:109]
	v_mfma_f32_16x16x32_bf16 v[106:109], v[162:165], v[194:197], v[106:109]
	v_mfma_f32_16x16x32_bf16 v[92:95], v[144:147], v[206:209], v[92:95]
	v_mfma_f32_16x16x32_bf16 v[92:95], v[154:157], v[210:213], v[92:95]
	v_mfma_f32_16x16x32_bf16 v[88:91], v[158:161], v[206:209], v[88:91]
	v_mfma_f32_16x16x32_bf16 v[88:91], v[162:165], v[210:213], v[88:91]
	v_mfma_f32_16x16x32_bf16 v[76:79], v[144:147], v[222:225], v[76:79]
	v_mfma_f32_16x16x32_bf16 v[76:79], v[154:157], v[226:229], v[76:79]
	v_mfma_f32_16x16x32_bf16 v[72:75], v[158:161], v[222:225], v[72:75]
	v_mfma_f32_16x16x32_bf16 v[72:75], v[162:165], v[226:229], v[72:75]
	s_setprio 0
	s_setprio 1
	v_mfma_f32_16x16x32_bf16 v[118:121], v[166:169], v[182:185], v[118:121]
	v_mfma_f32_16x16x32_bf16 v[118:121], v[170:173], v[186:189], v[118:121]
	v_mfma_f32_16x16x32_bf16 v[114:117], v[174:177], v[182:185], v[114:117]
	v_mfma_f32_16x16x32_bf16 v[114:117], v[178:181], v[186:189], v[114:117]
	v_mfma_f32_16x16x32_bf16 v[102:105], v[166:169], v[190:193], v[102:105]
	v_mfma_f32_16x16x32_bf16 v[102:105], v[170:173], v[194:197], v[102:105]
	v_mfma_f32_16x16x32_bf16 v[98:101], v[174:177], v[190:193], v[98:101]
	v_mfma_f32_16x16x32_bf16 v[98:101], v[178:181], v[194:197], v[98:101]
	v_mfma_f32_16x16x32_bf16 v[84:87], v[166:169], v[206:209], v[84:87]
	v_mfma_f32_16x16x32_bf16 v[84:87], v[170:173], v[210:213], v[84:87]
	v_mfma_f32_16x16x32_bf16 v[80:83], v[174:177], v[206:209], v[80:83]
	v_mfma_f32_16x16x32_bf16 v[80:83], v[178:181], v[210:213], v[80:83]
	v_mfma_f32_16x16x32_bf16 v[68:71], v[166:169], v[222:225], v[68:71]
	v_mfma_f32_16x16x32_bf16 v[68:71], v[170:173], v[226:229], v[68:71]
	v_mfma_f32_16x16x32_bf16 v[64:67], v[174:177], v[222:225], v[64:67]
	v_mfma_f32_16x16x32_bf16 v[64:67], v[178:181], v[226:229], v[64:67]
	s_setprio 0
	s_barrier
	s_add_i32 s42, s48, s88
	s_mov_b32 m0, s42
	ds_read_b128 v[182:185], v153 offset:16384
	ds_read_b128 v[186:189], v153 offset:17408
	ds_read_b128 v[190:193], v153 offset:18432
	ds_read_b128 v[194:197], v153 offset:19456
	ds_read_b128 v[206:209], v153 offset:20480
	ds_read_b128 v[210:213], v153 offset:21504
	ds_read_b128 v[222:225], v153 offset:22528
	ds_read_b128 v[226:229], v153 offset:23552
	global_load_lds_dwordx4 v132, s[44:45]
	s_add_i32 m0, s42, 0x2000
	s_add_u32 s42, s44, 0x28000
	s_addc_u32 s43, s45, 0
	s_add_i32 s28, s28, s88
	global_load_lds_dwordx4 v136, s[44:45]
	s_mov_b32 m0, s28
	s_nop 0
	global_load_lds_dwordx4 v132, s[42:43]
	s_add_i32 m0, s28, 0x2000
	s_nop 0
	global_load_lds_dwordx4 v136, s[42:43]
	s_mov_b32 m0, s89
	s_nop 0
	global_load_lds_dwordx4 v130, s[46:47]
	s_mov_b32 m0, s90
	s_nop 0
	global_load_lds_dwordx4 v134, s[46:47]
	s_waitcnt vmcnt(8)
	s_waitcnt lgkmcnt(0)
	s_barrier
	s_setprio 1
	s_waitcnt lgkmcnt(0)
	v_mfma_f32_16x16x32_bf16 v[60:63], v[144:147], v[182:185], v[60:63]
	v_mfma_f32_16x16x32_bf16 v[60:63], v[154:157], v[186:189], v[60:63]
	v_mfma_f32_16x16x32_bf16 v[56:59], v[158:161], v[182:185], v[56:59]
	v_mfma_f32_16x16x32_bf16 v[56:59], v[162:165], v[186:189], v[56:59]
	v_mfma_f32_16x16x32_bf16 v[44:47], v[144:147], v[190:193], v[44:47]
	v_mfma_f32_16x16x32_bf16 v[44:47], v[154:157], v[194:197], v[44:47]
	v_mfma_f32_16x16x32_bf16 v[40:43], v[158:161], v[190:193], v[40:43]
	v_mfma_f32_16x16x32_bf16 v[40:43], v[162:165], v[194:197], v[40:43]
	v_mfma_f32_16x16x32_bf16 v[28:31], v[144:147], v[206:209], v[28:31]
	v_mfma_f32_16x16x32_bf16 v[28:31], v[154:157], v[210:213], v[28:31]
	v_mfma_f32_16x16x32_bf16 v[24:27], v[158:161], v[206:209], v[24:27]
	v_mfma_f32_16x16x32_bf16 v[24:27], v[162:165], v[210:213], v[24:27]
	v_mfma_f32_16x16x32_bf16 v[12:15], v[144:147], v[222:225], v[12:15]
	v_mfma_f32_16x16x32_bf16 v[12:15], v[154:157], v[226:229], v[12:15]
	v_mfma_f32_16x16x32_bf16 v[8:11], v[158:161], v[222:225], v[8:11]
	v_mfma_f32_16x16x32_bf16 v[8:11], v[162:165], v[226:229], v[8:11]
	s_setprio 0
	s_setprio 1
	v_mfma_f32_16x16x32_bf16 v[52:55], v[166:169], v[182:185], v[52:55]
	v_mfma_f32_16x16x32_bf16 v[52:55], v[170:173], v[186:189], v[52:55]
	v_mfma_f32_16x16x32_bf16 v[48:51], v[174:177], v[182:185], v[48:51]
	v_mfma_f32_16x16x32_bf16 v[48:51], v[178:181], v[186:189], v[48:51]
	v_mfma_f32_16x16x32_bf16 v[36:39], v[166:169], v[190:193], v[36:39]
	v_mfma_f32_16x16x32_bf16 v[36:39], v[170:173], v[194:197], v[36:39]
	v_mfma_f32_16x16x32_bf16 v[32:35], v[174:177], v[190:193], v[32:35]
	v_mfma_f32_16x16x32_bf16 v[32:35], v[178:181], v[194:197], v[32:35]
	v_mfma_f32_16x16x32_bf16 v[20:23], v[166:169], v[206:209], v[20:23]
	v_mfma_f32_16x16x32_bf16 v[20:23], v[170:173], v[210:213], v[20:23]
	v_mfma_f32_16x16x32_bf16 v[16:19], v[174:177], v[206:209], v[16:19]
	v_mfma_f32_16x16x32_bf16 v[16:19], v[178:181], v[210:213], v[16:19]
	v_mfma_f32_16x16x32_bf16 v[4:7], v[166:169], v[222:225], v[4:7]
	v_mfma_f32_16x16x32_bf16 v[4:7], v[170:173], v[226:229], v[4:7]
	v_mfma_f32_16x16x32_bf16 v[0:3], v[174:177], v[222:225], v[0:3]
	v_mfma_f32_16x16x32_bf16 v[0:3], v[178:181], v[226:229], v[0:3]
	s_setprio 0
	s_barrier
; #define PG8_STAGE(bufoff, gbase, voff) do { _Pragma("unroll") for (int _i = 0; _i < 2; ++_i) \
;         __builtin_amdgcn_global_load_lds((const unsigned*)((const char*)(gbase) + (voff)[_i]), (PG8_LAS unsigned*)(lds + (bufoff) + ldsw + _i * 8192), 16, 0, 0); } while (0)
; #define PG8_LDA(dst, b, h) do { _Pragma("unroll") for (int m = 0; m < 4; ++m) _Pragma("unroll") for (int k = 0; k < 2; ++k) dst[m][k] = *(const PG8_LAS bf16x8*)(lds + PG8_SA(b, h) + aoff + m * 2048 + k * 1024); } while (0)
; #define PG8_LDB(dst, b, h) do { _Pragma("unroll") for (int n = 0; n < 2; ++n) _Pragma("unroll") for (int k = 0; k < 2; ++k) dst[n][k] = *(const PG8_LAS bf16x8*)(lds + PG8_SB(b, h) + boff + n * 2048 + k * 1024); } while (0)
; #define PG8_MMA(ai, bj, At, Bt) do { __builtin_amdgcn_s_setprio(1); _Pragma("unroll") for (int m = 0; m < 4; ++m) _Pragma("unroll") for (int n = 0; n < 2; ++n) _Pragma("unroll") for (int k = 0; k < 2; ++k) \
;         acc[ai][bj][m][n] = __builtin_amdgcn_mfma_f32_16x16x32_bf16(Bt[n][k], At[m][k], acc[ai][bj][m][n], 0, 0, 0); __builtin_amdgcn_s_setprio(0); } while (0)
; #define PG8_WAIT_V(n) asm volatile("s_waitcnt vmcnt(" #n ")" ::: "memory")
; #define PG8_WAIT_L(n) asm volatile("s_waitcnt lgkmcnt(" #n ")" ::: "memory")
; #define PG8_BAR __builtin_amdgcn_s_barrier()
; #define PG8_SCHED __builtin_amdgcn_sched_barrier(0)
; template <class Epi, class Sched, bool ALIGN_EPI = true, bool SP2 = true>
; __device__ __forceinline__ void gemm_phase(PG8_LAS unsigned char* lds, const Gemm g, const Sched& S, const Epi& E, const int tid) {
;     ...
;             PG8_LDB(B0, 1, 0); PG8_LDB(B1, 1, 1); PG8_SCHED; PG8_LDA(At, 1, 0); PG8_STAGE(PG8_SA(0, 1), a2 + hstepA, voffA);
;             PG8_WAIT_V(8); PG8_WAIT_L(0); PG8_BAR; PG8_MMA(0, 0, At, B0); PG8_MMA(0, 1, At, B1); PG8_BAR; PG8_SCHED;
;             PG8_LDA(At, 1, 1); PG8_STAGE(PG8_SB(1, 0), b3, voffB); PG8_STAGE(PG8_SB(1, 1), b3 + hstepB, voffB); PG8_STAGE(PG8_SA(1, 0), a3, voffA);
;             PG8_WAIT_V(8); PG8_WAIT_L(0); PG8_BAR; PG8_MMA(1, 0, At, B0); PG8_MMA(1, 1, At, B1); PG8_BAR; PG8_SCHED;
	s_add_i32 s28, 0, 0x18000
	s_add_i32 s48, 0, 0x1c000
	v_add_u32_e32 v162, s28, v152
	v_add_u32_e32 v178, s48, v152
	ds_read_b128 v[144:147], v162
	ds_read_b128 v[154:157], v162 offset:1024
	ds_read_b128 v[158:161], v162 offset:2048
	ds_read_b128 v[162:165], v162 offset:3072
	ds_read_b128 v[166:169], v178
	ds_read_b128 v[170:173], v178 offset:1024
	ds_read_b128 v[174:177], v178 offset:2048
	ds_read_b128 v[178:181], v178 offset:3072
	s_add_u32 s42, s46, 0x150000
	s_addc_u32 s43, s47, 0
	s_mov_b32 m0, s91
	ds_read_b128 v[182:185], v153 offset:32768
	ds_read_b128 v[186:189], v153 offset:33792
	ds_read_b128 v[190:193], v153 offset:34816
	ds_read_b128 v[194:197], v153 offset:35840
	ds_read_b128 v[206:209], v153 offset:36864
	ds_read_b128 v[210:213], v153 offset:37888
	ds_read_b128 v[222:225], v153 offset:38912
	ds_read_b128 v[226:229], v153 offset:39936
	global_load_lds_dwordx4 v130, s[42:43]
	s_mov_b32 m0, s80
	s_nop 0
	global_load_lds_dwordx4 v134, s[42:43]
	s_waitcnt vmcnt(8)
	s_waitcnt lgkmcnt(0)
	s_barrier
	s_setprio 1
	s_waitcnt lgkmcnt(0)
	v_mfma_f32_16x16x32_bf16 v[126:129], v[144:147], v[182:185], v[126:129]
	v_mfma_f32_16x16x32_bf16 v[126:129], v[154:157], v[186:189], v[126:129]
	v_mfma_f32_16x16x32_bf16 v[122:125], v[158:161], v[182:185], v[122:125]
	v_mfma_f32_16x16x32_bf16 v[122:125], v[162:165], v[186:189], v[122:125]
	v_mfma_f32_16x16x32_bf16 v[110:113], v[144:147], v[190:193], v[110:113]
	v_mfma_f32_16x16x32_bf16 v[110:113], v[154:157], v[194:197], v[110:113]
	v_mfma_f32_16x16x32_bf16 v[106:109], v[158:161], v[190:193], v[106:109]
	v_mfma_f32_16x16x32_bf16 v[106:109], v[162:165], v[194:197], v[106:109]
	v_mfma_f32_16x16x32_bf16 v[92:95], v[144:147], v[206:209], v[92:95]
	v_mfma_f32_16x16x32_bf16 v[92:95], v[154:157], v[210:213], v[92:95]
	v_mfma_f32_16x16x32_bf16 v[88:91], v[158:161], v[206:209], v[88:91]
	v_mfma_f32_16x16x32_bf16 v[88:91], v[162:165], v[210:213], v[88:91]
	v_mfma_f32_16x16x32_bf16 v[76:79], v[144:147], v[222:225], v[76:79]
	v_mfma_f32_16x16x32_bf16 v[76:79], v[154:157], v[226:229], v[76:79]
	v_mfma_f32_16x16x32_bf16 v[72:75], v[158:161], v[222:225], v[72:75]
	v_mfma_f32_16x16x32_bf16 v[72:75], v[162:165], v[226:229], v[72:75]
	s_setprio 0
	s_setprio 1
	v_mfma_f32_16x16x32_bf16 v[118:121], v[166:169], v[182:185], v[118:121]
	v_mfma_f32_16x16x32_bf16 v[118:121], v[170:173], v[186:189], v[118:121]
	v_mfma_f32_16x16x32_bf16 v[114:117], v[174:177], v[182:185], v[114:117]
	v_mfma_f32_16x16x32_bf16 v[114:117], v[178:181], v[186:189], v[114:117]
	v_mfma_f32_16x16x32_bf16 v[102:105], v[166:169], v[190:193], v[102:105]
	v_mfma_f32_16x16x32_bf16 v[102:105], v[170:173], v[194:197], v[102:105]
	v_mfma_f32_16x16x32_bf16 v[98:101], v[174:177], v[190:193], v[98:101]
	v_mfma_f32_16x16x32_bf16 v[98:101], v[178:181], v[194:197], v[98:101]
	v_mfma_f32_16x16x32_bf16 v[84:87], v[166:169], v[206:209], v[84:87]
	v_mfma_f32_16x16x32_bf16 v[84:87], v[170:173], v[210:213], v[84:87]
	v_mfma_f32_16x16x32_bf16 v[80:83], v[174:177], v[206:209], v[80:83]
	v_mfma_f32_16x16x32_bf16 v[80:83], v[178:181], v[210:213], v[80:83]
	v_mfma_f32_16x16x32_bf16 v[68:71], v[166:169], v[222:225], v[68:71]
	v_mfma_f32_16x16x32_bf16 v[68:71], v[170:173], v[226:229], v[68:71]
	v_mfma_f32_16x16x32_bf16 v[64:67], v[174:177], v[222:225], v[64:67]
	v_mfma_f32_16x16x32_bf16 v[64:67], v[178:181], v[226:229], v[64:67]
	s_setprio 0
	s_barrier
	s_add_i32 s28, s28, s88
	s_add_u32 s4, s44, 0x80
	s_addc_u32 s5, s45, 0
	s_mov_b32 m0, s28
	ds_read_b128 v[182:185], v153 offset:49152
	ds_read_b128 v[186:189], v153 offset:50176
	ds_read_b128 v[190:193], v153 offset:51200
	ds_read_b128 v[194:197], v153 offset:52224
	ds_read_b128 v[206:209], v153 offset:53248
	ds_read_b128 v[210:213], v153 offset:54272
	ds_read_b128 v[222:225], v153 offset:55296
	ds_read_b128 v[226:229], v153 offset:56320
	global_load_lds_dwordx4 v132, s[4:5]
	s_add_i32 m0, s28, 0x2000
	s_add_u32 s42, s44, 0x28080
	s_addc_u32 s43, s45, 0
	s_add_i32 s28, s48, s88
	global_load_lds_dwordx4 v136, s[4:5]
	s_mov_b32 m0, s28
	s_nop 0
	global_load_lds_dwordx4 v132, s[42:43]
	s_add_i32 m0, s28, 0x2000
	s_nop 0
	global_load_lds_dwordx4 v136, s[42:43]
	s_add_u32 s4, s46, 0x80
	s_addc_u32 s5, s47, 0
	s_mov_b32 m0, s56
	s_nop 0
	global_load_lds_dwordx4 v130, s[4:5]
	s_mov_b32 m0, s57
	s_nop 0
	global_load_lds_dwordx4 v134, s[4:5]
	s_waitcnt vmcnt(8)
	s_waitcnt lgkmcnt(0)
	s_barrier
	s_setprio 1
	s_waitcnt lgkmcnt(0)
	v_mfma_f32_16x16x32_bf16 v[60:63], v[144:147], v[182:185], v[60:63]
	v_mfma_f32_16x16x32_bf16 v[60:63], v[154:157], v[186:189], v[60:63]
	v_mfma_f32_16x16x32_bf16 v[56:59], v[158:161], v[182:185], v[56:59]
	v_mfma_f32_16x16x32_bf16 v[56:59], v[162:165], v[186:189], v[56:59]
	v_mfma_f32_16x16x32_bf16 v[44:47], v[144:147], v[190:193], v[44:47]
	v_mfma_f32_16x16x32_bf16 v[44:47], v[154:157], v[194:197], v[44:47]
	v_mfma_f32_16x16x32_bf16 v[40:43], v[158:161], v[190:193], v[40:43]
	v_mfma_f32_16x16x32_bf16 v[40:43], v[162:165], v[194:197], v[40:43]
	v_mfma_f32_16x16x32_bf16 v[28:31], v[144:147], v[206:209], v[28:31]
	v_mfma_f32_16x16x32_bf16 v[28:31], v[154:157], v[210:213], v[28:31]
	v_mfma_f32_16x16x32_bf16 v[24:27], v[158:161], v[206:209], v[24:27]
	v_mfma_f32_16x16x32_bf16 v[24:27], v[162:165], v[210:213], v[24:27]
	v_mfma_f32_16x16x32_bf16 v[12:15], v[144:147], v[222:225], v[12:15]
	v_mfma_f32_16x16x32_bf16 v[12:15], v[154:157], v[226:229], v[12:15]
	v_mfma_f32_16x16x32_bf16 v[8:11], v[158:161], v[222:225], v[8:11]
	v_mfma_f32_16x16x32_bf16 v[8:11], v[162:165], v[226:229], v[8:11]
	s_setprio 0
	s_setprio 1
	v_mfma_f32_16x16x32_bf16 v[52:55], v[166:169], v[182:185], v[52:55]
	v_mfma_f32_16x16x32_bf16 v[52:55], v[170:173], v[186:189], v[52:55]
	v_mfma_f32_16x16x32_bf16 v[48:51], v[174:177], v[182:185], v[48:51]
	v_mfma_f32_16x16x32_bf16 v[48:51], v[178:181], v[186:189], v[48:51]
	v_mfma_f32_16x16x32_bf16 v[36:39], v[166:169], v[190:193], v[36:39]
	v_mfma_f32_16x16x32_bf16 v[36:39], v[170:173], v[194:197], v[36:39]
	v_mfma_f32_16x16x32_bf16 v[32:35], v[174:177], v[190:193], v[32:35]
	v_mfma_f32_16x16x32_bf16 v[32:35], v[178:181], v[194:197], v[32:35]
	v_mfma_f32_16x16x32_bf16 v[20:23], v[166:169], v[206:209], v[20:23]
	v_mfma_f32_16x16x32_bf16 v[20:23], v[170:173], v[210:213], v[20:23]
	v_mfma_f32_16x16x32_bf16 v[16:19], v[174:177], v[206:209], v[16:19]
	v_mfma_f32_16x16x32_bf16 v[16:19], v[178:181], v[210:213], v[16:19]
	v_mfma_f32_16x16x32_bf16 v[4:7], v[166:169], v[222:225], v[4:7]
	v_mfma_f32_16x16x32_bf16 v[4:7], v[170:173], v[226:229], v[4:7]
	v_mfma_f32_16x16x32_bf16 v[0:3], v[174:177], v[222:225], v[0:3]
	v_mfma_f32_16x16x32_bf16 v[0:3], v[178:181], v[226:229], v[0:3]
	s_setprio 0
	s_barrier
	s_add_u32 s26, s26, 0x100
	s_addc_u32 s27, s27, 0
	s_cmp_ge_i32 s29, s24
	s_mov_b64 s[42:43], s[40:41]
	s_mov_b32 s28, s29
	s_cbranch_scc0 .LBB0_700
	s_mov_b64 s[4:5], 0x80
	s_and_b64 vcc, exec, s[64:65]
	s_cbranch_vccz .LBB0_703
	s_barrier

; #define PG8_STAGE(bufoff, gbase, voff) do { _Pragma("unroll") for (int _i = 0; _i < 2; ++_i) \
;         __builtin_amdgcn_global_load_lds((const unsigned*)((const char*)(gbase) + (voff)[_i]), (PG8_LAS unsigned*)(lds + (bufoff) + ldsw + _i * 8192), 16, 0, 0); } while (0)
; #define PG8_LDA(dst, b, h) do { _Pragma("unroll") for (int m = 0; m < 4; ++m) _Pragma("unroll") for (int k = 0; k < 2; ++k) dst[m][k] = *(const PG8_LAS bf16x8*)(lds + PG8_SA(b, h) + aoff + m * 2048 + k * 1024); } while (0)
; #define PG8_LDB(dst, b, h) do { _Pragma("unroll") for (int n = 0; n < 2; ++n) _Pragma("unroll") for (int k = 0; k < 2; ++k) dst[n][k] = *(const PG8_LAS bf16x8*)(lds + PG8_SB(b, h) + boff + n * 2048 + k * 1024); } while (0)
; #define PG8_MMA(ai, bj, At, Bt) do { __builtin_amdgcn_s_setprio(1); _Pragma("unroll") for (int m = 0; m < 4; ++m) _Pragma("unroll") for (int n = 0; n < 2; ++n) _Pragma("unroll") for (int k = 0; k < 2; ++k) \
;         acc[ai][bj][m][n] = __builtin_amdgcn_mfma_f32_16x16x32_bf16(Bt[n][k], At[m][k], acc[ai][bj][m][n], 0, 0, 0); __builtin_amdgcn_s_setprio(0); } while (0)
; #define PG8_WAIT_V(n) asm volatile("s_waitcnt vmcnt(" #n ")" ::: "memory")
; #define PG8_WAIT_L(n) asm volatile("s_waitcnt lgkmcnt(" #n ")" ::: "memory")
; template <class Epi, class Sched, bool ALIGN_EPI = true, bool SP2 = true>
; __device__ __forceinline__ void gemm_phase(PG8_LAS unsigned char* lds, const Gemm g, const Sched& S, const Epi& E, const int tid) {
;     ...
;             const bool last = (t == nt - 2);
;             const char* a1 = cA + (size_t)(t + 1) * kstep;
;             const char* a2 = last ? nA : cA + (size_t)(t + 2) * kstep; const char* b2 = last ? nB : cB + (size_t)(t + 2) * kstep;
;             const char* a3 = a2 + kstep; const char* b3 = b2 + kstep;
;             if (last && has_next) S.a_ready(nxt);
;             if constexpr (SP2) {
;             PG8_LDB(B0, 0, 0); PG8_LDB(B1, 0, 1); PG8_SCHED; PG8_LDA(At, 0, 0); PG8_STAGE(PG8_SA(1, 1), a1 + hstepA, voffA);
;             PG8_WAIT_V(8); PG8_WAIT_L(0); PG8_BAR; PG8_MMA(0, 0, At, B0); PG8_MMA(0, 1, At, B1); PG8_BAR; PG8_SCHED;
;             PG8_LDA(At, 0, 1); PG8_STAGE(PG8_SB(0, 0), b2, voffB); PG8_STAGE(PG8_SB(0, 1), b2 + hstepB, voffB); PG8_STAGE(PG8_SA(0, 0), a2, voffA);
;             PG8_WAIT_V(8); PG8_WAIT_L(0); PG8_BAR; PG8_MMA(1, 0, At, B0); PG8_MMA(1, 1, At, B1); PG8_BAR; PG8_SCHED;
.LBB0_1077:
	s_add_i32 s63, s82, 2
	s_add_u32 s83, s80, 0xfff80080
	s_addc_u32 s84, s81, -1
	s_add_i32 vcc_lo, 0, 0x10000
	s_cmp_eq_u32 s29, s82
	s_cselect_b32 s85, s67, s84
	s_cselect_b32 s84, s66, s83
	v_add_u32_e32 v96, vcc_lo, v141
	s_cselect_b32 s83, s69, s61
	s_cselect_b32 s82, s68, s59
	s_add_i32 s30, 0, 0x14000
	ds_read_b128 v[146:149], v96
	ds_read_b128 v[150:153], v96 offset:1024
	ds_read_b128 v[154:157], v96 offset:2048
	ds_read_b128 v[158:161], v96 offset:3072
	v_add_u32_e32 v96, s30, v141
	ds_read_b128 v[162:165], v96
	ds_read_b128 v[166:169], v96 offset:1024
	ds_read_b128 v[170:173], v96 offset:2048
	ds_read_b128 v[174:177], v96 offset:3072
	s_add_i32 m0, s25, 0xc000
	ds_read_b128 v[178:181], v145
	ds_read_b128 v[182:185], v145 offset:1024
	ds_read_b128 v[186:189], v145 offset:2048
	ds_read_b128 v[190:193], v145 offset:3072
	ds_read_b128 v[194:197], v145 offset:4096
	ds_read_b128 v[200:203], v145 offset:5120
	ds_read_b128 v[206:209], v145 offset:6144
	ds_read_b128 v[210:213], v145 offset:7168
	global_load_lds_dwordx4 v136, s[80:81]
	s_add_i32 m0, s25, 0xe000
	s_nop 0
	global_load_lds_dwordx4 v138, s[80:81]
	s_waitcnt vmcnt(8)
	s_waitcnt lgkmcnt(0)
	s_barrier
	s_setprio 1
	s_waitcnt lgkmcnt(0)
	v_mfma_f32_16x16x32_bf16 v[92:95], v[146:149], v[178:181], v[92:95]
	v_mfma_f32_16x16x32_bf16 v[92:95], v[150:153], v[182:185], v[92:95]
	ds_read_b128 v[224:227], v145 offset:16384
	v_mfma_f32_16x16x32_bf16 v[130:133], v[154:157], v[178:181], v[130:133]
	v_mfma_f32_16x16x32_bf16 v[130:133], v[158:161], v[182:185], v[130:133]
	v_mfma_f32_16x16x32_bf16 v[126:129], v[146:149], v[186:189], v[126:129]
	v_mfma_f32_16x16x32_bf16 v[126:129], v[150:153], v[190:193], v[126:129]
	ds_read_b128 v[228:231], v145 offset:17408
	v_mfma_f32_16x16x32_bf16 v[122:125], v[154:157], v[186:189], v[122:125]
	v_mfma_f32_16x16x32_bf16 v[122:125], v[158:161], v[190:193], v[122:125]
	v_mfma_f32_16x16x32_bf16 v[118:121], v[146:149], v[194:197], v[118:121]
	v_mfma_f32_16x16x32_bf16 v[118:121], v[150:153], v[200:203], v[118:121]
	ds_read_b128 v[232:235], v145 offset:18432
	v_mfma_f32_16x16x32_bf16 v[110:113], v[154:157], v[194:197], v[110:113]
	v_mfma_f32_16x16x32_bf16 v[110:113], v[158:161], v[200:203], v[110:113]
	v_mfma_f32_16x16x32_bf16 v[76:79], v[146:149], v[206:209], v[76:79]
	v_mfma_f32_16x16x32_bf16 v[76:79], v[150:153], v[210:213], v[76:79]
	ds_read_b128 v[236:239], v145 offset:19456
	v_mfma_f32_16x16x32_bf16 v[72:75], v[154:157], v[206:209], v[72:75]
	v_mfma_f32_16x16x32_bf16 v[72:75], v[158:161], v[210:213], v[72:75]
	s_setprio 0
	s_setprio 1
	v_mfma_f32_16x16x32_bf16 v[88:91], v[162:165], v[178:181], v[88:91]
	v_mfma_f32_16x16x32_bf16 v[88:91], v[166:169], v[182:185], v[88:91]
	ds_read_b128 v[240:243], v145 offset:20480
	v_mfma_f32_16x16x32_bf16 v[84:87], v[170:173], v[178:181], v[84:87]
	v_mfma_f32_16x16x32_bf16 v[84:87], v[174:177], v[182:185], v[84:87]
	v_mfma_f32_16x16x32_bf16 v[114:117], v[162:165], v[186:189], v[114:117]
	v_mfma_f32_16x16x32_bf16 v[114:117], v[166:169], v[190:193], v[114:117]
	ds_read_b128 v[244:247], v145 offset:21504
	v_mfma_f32_16x16x32_bf16 v[106:109], v[170:173], v[186:189], v[106:109]
	v_mfma_f32_16x16x32_bf16 v[106:109], v[174:177], v[190:193], v[106:109]
	v_mfma_f32_16x16x32_bf16 v[102:105], v[162:165], v[194:197], v[102:105]
	v_mfma_f32_16x16x32_bf16 v[102:105], v[166:169], v[200:203], v[102:105]
	ds_read_b128 v[248:251], v145 offset:22528
	v_mfma_f32_16x16x32_bf16 v[80:83], v[170:173], v[194:197], v[80:83]
	v_mfma_f32_16x16x32_bf16 v[80:83], v[174:177], v[200:203], v[80:83]
	v_mfma_f32_16x16x32_bf16 v[68:71], v[162:165], v[206:209], v[68:71]
	v_mfma_f32_16x16x32_bf16 v[68:71], v[166:169], v[210:213], v[68:71]
	v_mfma_f32_16x16x32_bf16 v[64:67], v[170:173], v[206:209], v[64:67]
	v_mfma_f32_16x16x32_bf16 v[64:67], v[174:177], v[210:213], v[64:67]
	s_setprio 0
	s_barrier
	s_add_i32 s31, vcc_lo, s24
	s_mov_b32 m0, s31
	ds_read_b128 v[210:213], v145 offset:23552
	global_load_lds_dwordx4 v100, s[82:83]
	s_add_i32 m0, s31, 0x2000
	s_add_u32 vcc_lo, s82, 0x80000
	s_addc_u32 vcc_hi, s83, 0
	s_add_i32 s30, s30, s24
	global_load_lds_dwordx4 v134, s[82:83]
	s_mov_b32 m0, s30
	s_nop 0
	global_load_lds_dwordx4 v100, vcc
	s_add_i32 m0, s30, 0x2000
	s_nop 0
	global_load_lds_dwordx4 v134, vcc
	s_mov_b32 m0, s25
	s_nop 0
	global_load_lds_dwordx4 v100, s[84:85]
	s_mov_b32 m0, s49
	s_nop 0
	global_load_lds_dwordx4 v134, s[84:85]
	s_waitcnt vmcnt(6)
	s_waitcnt lgkmcnt(0)
	s_barrier
	s_setprio 1
	s_waitcnt lgkmcnt(0)
	v_mfma_f32_16x16x32_bf16 v[56:59], v[146:149], v[224:227], v[56:59]
	v_mfma_f32_16x16x32_bf16 v[56:59], v[150:153], v[228:231], v[56:59]
	v_mfma_f32_16x16x32_bf16 v[60:63], v[154:157], v[224:227], v[60:63]
	v_mfma_f32_16x16x32_bf16 v[60:63], v[158:161], v[228:231], v[60:63]
	v_mfma_f32_16x16x32_bf16 v[44:47], v[146:149], v[232:235], v[44:47]
	v_mfma_f32_16x16x32_bf16 v[44:47], v[150:153], v[236:239], v[44:47]
	v_mfma_f32_16x16x32_bf16 v[40:43], v[154:157], v[232:235], v[40:43]
	v_mfma_f32_16x16x32_bf16 v[40:43], v[158:161], v[236:239], v[40:43]
	v_mfma_f32_16x16x32_bf16 v[28:31], v[146:149], v[240:243], v[28:31]
	v_mfma_f32_16x16x32_bf16 v[28:31], v[150:153], v[244:247], v[28:31]
	v_mfma_f32_16x16x32_bf16 v[24:27], v[154:157], v[240:243], v[24:27]
	v_mfma_f32_16x16x32_bf16 v[24:27], v[158:161], v[244:247], v[24:27]
	v_mfma_f32_16x16x32_bf16 v[12:15], v[146:149], v[248:251], v[12:15]
	v_mfma_f32_16x16x32_bf16 v[12:15], v[150:153], v[210:213], v[12:15]
	v_mfma_f32_16x16x32_bf16 v[8:11], v[154:157], v[248:251], v[8:11]
	v_mfma_f32_16x16x32_bf16 v[8:11], v[158:161], v[210:213], v[8:11]
	s_setprio 0
	s_setprio 1
	v_mfma_f32_16x16x32_bf16 v[52:55], v[162:165], v[224:227], v[52:55]
	v_mfma_f32_16x16x32_bf16 v[52:55], v[166:169], v[228:231], v[52:55]
	v_mfma_f32_16x16x32_bf16 v[48:51], v[170:173], v[224:227], v[48:51]
	v_mfma_f32_16x16x32_bf16 v[48:51], v[174:177], v[228:231], v[48:51]
	v_mfma_f32_16x16x32_bf16 v[36:39], v[162:165], v[232:235], v[36:39]
	v_mfma_f32_16x16x32_bf16 v[36:39], v[166:169], v[236:239], v[36:39]
	v_mfma_f32_16x16x32_bf16 v[32:35], v[170:173], v[232:235], v[32:35]
	v_mfma_f32_16x16x32_bf16 v[32:35], v[174:177], v[236:239], v[32:35]
	v_mfma_f32_16x16x32_bf16 v[20:23], v[162:165], v[240:243], v[20:23]
	v_mfma_f32_16x16x32_bf16 v[20:23], v[166:169], v[244:247], v[20:23]
	v_mfma_f32_16x16x32_bf16 v[16:19], v[170:173], v[240:243], v[16:19]
	v_mfma_f32_16x16x32_bf16 v[16:19], v[174:177], v[244:247], v[16:19]
	v_mfma_f32_16x16x32_bf16 v[4:7], v[162:165], v[248:251], v[4:7]
	v_mfma_f32_16x16x32_bf16 v[4:7], v[166:169], v[210:213], v[4:7]
	v_mfma_f32_16x16x32_bf16 v[0:3], v[170:173], v[248:251], v[0:3]
	v_mfma_f32_16x16x32_bf16 v[0:3], v[174:177], v[210:213], v[0:3]
	s_setprio 0
	s_barrier
; #define PG8_STAGE(bufoff, gbase, voff) do { _Pragma("unroll") for (int _i = 0; _i < 2; ++_i) \
;         __builtin_amdgcn_global_load_lds((const unsigned*)((const char*)(gbase) + (voff)[_i]), (PG8_LAS unsigned*)(lds + (bufoff) + ldsw + _i * 8192), 16, 0, 0); } while (0)
; #define PG8_LDA(dst, b, h) do { _Pragma("unroll") for (int m = 0; m < 4; ++m) _Pragma("unroll") for (int k = 0; k < 2; ++k) dst[m][k] = *(const PG8_LAS bf16x8*)(lds + PG8_SA(b, h) + aoff + m * 2048 + k * 1024); } while (0)
; #define PG8_LDB(dst, b, h) do { _Pragma("unroll") for (int n = 0; n < 2; ++n) _Pragma("unroll") for (int k = 0; k < 2; ++k) dst[n][k] = *(const PG8_LAS bf16x8*)(lds + PG8_SB(b, h) + boff + n * 2048 + k * 1024); } while (0)
; #define PG8_MMA(ai, bj, At, Bt) do { __builtin_amdgcn_s_setprio(1); _Pragma("unroll") for (int m = 0; m < 4; ++m) _Pragma("unroll") for (int n = 0; n < 2; ++n) _Pragma("unroll") for (int k = 0; k < 2; ++k) \
;         acc[ai][bj][m][n] = __builtin_amdgcn_mfma_f32_16x16x32_bf16(Bt[n][k], At[m][k], acc[ai][bj][m][n], 0, 0, 0); __builtin_amdgcn_s_setprio(0); } while (0)
; #define PG8_WAIT_V(n) asm volatile("s_waitcnt vmcnt(" #n ")" ::: "memory")
; #define PG8_WAIT_L(n) asm volatile("s_waitcnt lgkmcnt(" #n ")" ::: "memory")
; #define PG8_BAR __builtin_amdgcn_s_barrier()
; template <class Epi, class Sched, bool ALIGN_EPI = true, bool SP2 = true>
; __device__ __forceinline__ void gemm_phase(PG8_LAS unsigned char* lds, const Gemm g, const Sched& S, const Epi& E, const int tid) {
;     ...
;         for (int t = 0; t < nt; t += 2) {
;             const bool last = (t == nt - 2);
;             const char* a1 = cA + (size_t)(t + 1) * kstep;
;             const char* a2 = last ? nA : cA + (size_t)(t + 2) * kstep; const char* b2 = last ? nB : cB + (size_t)(t + 2) * kstep;
;             const char* a3 = a2 + kstep; const char* b3 = b2 + kstep;
;     ...
;             PG8_LDB(B0, 1, 0); PG8_LDB(B1, 1, 1); PG8_SCHED; PG8_LDA(At, 1, 0); PG8_STAGE(PG8_SA(0, 1), a2 + hstepA, voffA);
;             PG8_WAIT_V(8); PG8_WAIT_L(0); PG8_BAR; PG8_MMA(0, 0, At, B0); PG8_MMA(0, 1, At, B1); PG8_BAR; PG8_SCHED;
;             PG8_LDA(At, 1, 1); PG8_STAGE(PG8_SB(1, 0), b3, voffB); PG8_STAGE(PG8_SB(1, 1), b3 + hstepB, voffB); PG8_STAGE(PG8_SA(1, 0), a3, voffA);
;             PG8_WAIT_V(8); PG8_WAIT_L(0); PG8_BAR; PG8_MMA(1, 0, At, B0); PG8_MMA(1, 1, At, B1); PG8_BAR; PG8_SCHED;
	s_add_i32 s30, 0, 0x18000
	v_add_u32_e32 v96, s30, v141
	s_add_i32 s31, 0, 0x1c000
	ds_read_b128 v[146:149], v96
	ds_read_b128 v[150:153], v96 offset:1024
	ds_read_b128 v[154:157], v96 offset:2048
	ds_read_b128 v[158:161], v96 offset:3072
	v_add_u32_e32 v96, s31, v141
	ds_read_b128 v[162:165], v96
	ds_read_b128 v[166:169], v96 offset:1024
	ds_read_b128 v[170:173], v96 offset:2048
	ds_read_b128 v[174:177], v96 offset:3072
	s_add_u32 s84, s84, 0x80000
	s_addc_u32 s85, s85, 0
	s_mov_b32 m0, s51
	ds_read_b128 v[178:181], v145 offset:32768
	ds_read_b128 v[182:185], v145 offset:33792
	ds_read_b128 v[186:189], v145 offset:34816
	ds_read_b128 v[190:193], v145 offset:35840
	ds_read_b128 v[194:197], v145 offset:36864
	ds_read_b128 v[200:203], v145 offset:37888
	ds_read_b128 v[206:209], v145 offset:38912
	ds_read_b128 v[210:213], v145 offset:39936
	global_load_lds_dwordx4 v100, s[84:85]
	s_mov_b32 m0, s76
	s_nop 0
	global_load_lds_dwordx4 v134, s[84:85]
	s_waitcnt vmcnt(8)
	s_waitcnt lgkmcnt(0)
	s_barrier
	s_setprio 1
	s_waitcnt lgkmcnt(0)
	v_mfma_f32_16x16x32_bf16 v[92:95], v[146:149], v[178:181], v[92:95]
	v_mfma_f32_16x16x32_bf16 v[92:95], v[150:153], v[182:185], v[92:95]
	ds_read_b128 v[224:227], v145 offset:49152
	v_mfma_f32_16x16x32_bf16 v[130:133], v[154:157], v[178:181], v[130:133]
	v_mfma_f32_16x16x32_bf16 v[130:133], v[158:161], v[182:185], v[130:133]
	v_mfma_f32_16x16x32_bf16 v[126:129], v[146:149], v[186:189], v[126:129]
	v_mfma_f32_16x16x32_bf16 v[126:129], v[150:153], v[190:193], v[126:129]
	ds_read_b128 v[228:231], v145 offset:50176
	v_mfma_f32_16x16x32_bf16 v[122:125], v[154:157], v[186:189], v[122:125]
	v_mfma_f32_16x16x32_bf16 v[122:125], v[158:161], v[190:193], v[122:125]
	v_mfma_f32_16x16x32_bf16 v[118:121], v[146:149], v[194:197], v[118:121]
	v_mfma_f32_16x16x32_bf16 v[118:121], v[150:153], v[200:203], v[118:121]
	ds_read_b128 v[232:235], v145 offset:51200
	v_mfma_f32_16x16x32_bf16 v[110:113], v[154:157], v[194:197], v[110:113]
	v_mfma_f32_16x16x32_bf16 v[110:113], v[158:161], v[200:203], v[110:113]
	v_mfma_f32_16x16x32_bf16 v[76:79], v[146:149], v[206:209], v[76:79]
	v_mfma_f32_16x16x32_bf16 v[76:79], v[150:153], v[210:213], v[76:79]
	ds_read_b128 v[236:239], v145 offset:52224
	v_mfma_f32_16x16x32_bf16 v[72:75], v[154:157], v[206:209], v[72:75]
	v_mfma_f32_16x16x32_bf16 v[72:75], v[158:161], v[210:213], v[72:75]
	s_setprio 0
	s_setprio 1
	v_mfma_f32_16x16x32_bf16 v[88:91], v[162:165], v[178:181], v[88:91]
	v_mfma_f32_16x16x32_bf16 v[88:91], v[166:169], v[182:185], v[88:91]
	ds_read_b128 v[240:243], v145 offset:53248
	v_mfma_f32_16x16x32_bf16 v[84:87], v[170:173], v[178:181], v[84:87]
	v_mfma_f32_16x16x32_bf16 v[84:87], v[174:177], v[182:185], v[84:87]
	v_mfma_f32_16x16x32_bf16 v[114:117], v[162:165], v[186:189], v[114:117]
	v_mfma_f32_16x16x32_bf16 v[114:117], v[166:169], v[190:193], v[114:117]
	ds_read_b128 v[244:247], v145 offset:54272
	v_mfma_f32_16x16x32_bf16 v[106:109], v[170:173], v[186:189], v[106:109]
	v_mfma_f32_16x16x32_bf16 v[106:109], v[174:177], v[190:193], v[106:109]
	v_mfma_f32_16x16x32_bf16 v[102:105], v[162:165], v[194:197], v[102:105]
	v_mfma_f32_16x16x32_bf16 v[102:105], v[166:169], v[200:203], v[102:105]
	ds_read_b128 v[248:251], v145 offset:55296
	v_mfma_f32_16x16x32_bf16 v[80:83], v[170:173], v[194:197], v[80:83]
	v_mfma_f32_16x16x32_bf16 v[80:83], v[174:177], v[200:203], v[80:83]
	v_mfma_f32_16x16x32_bf16 v[68:71], v[162:165], v[206:209], v[68:71]
	v_mfma_f32_16x16x32_bf16 v[68:71], v[166:169], v[210:213], v[68:71]
	v_mfma_f32_16x16x32_bf16 v[64:67], v[170:173], v[206:209], v[64:67]
	v_mfma_f32_16x16x32_bf16 v[64:67], v[174:177], v[210:213], v[64:67]
	s_setprio 0
	s_barrier
	s_add_i32 s30, s30, s24
	s_add_u32 s4, s82, 0x80
	s_addc_u32 s5, s83, 0
	s_mov_b32 m0, s30
	ds_read_b128 v[210:213], v145 offset:56320
	global_load_lds_dwordx4 v100, s[4:5]
	s_add_i32 m0, s30, 0x2000
	s_add_u32 s82, s82, 0x80080
	s_addc_u32 s83, s83, 0
	s_add_i32 s30, s31, s24
	global_load_lds_dwordx4 v134, s[4:5]
	s_mov_b32 m0, s30
	s_nop 0
	global_load_lds_dwordx4 v100, s[82:83]
	s_add_i32 m0, s30, 0x2000
	s_nop 0
	global_load_lds_dwordx4 v134, s[82:83]
	s_add_u32 s4, s84, 0xfff80080
	s_addc_u32 s5, s85, -1
	s_mov_b32 m0, s90
	s_nop 0
	global_load_lds_dwordx4 v100, s[4:5]
	s_mov_b32 m0, s91
	s_nop 0
	global_load_lds_dwordx4 v134, s[4:5]
	s_waitcnt vmcnt(6)
	s_waitcnt lgkmcnt(0)
	s_barrier
	s_setprio 1
	s_waitcnt lgkmcnt(0)
	v_mfma_f32_16x16x32_bf16 v[56:59], v[146:149], v[224:227], v[56:59]
	v_mfma_f32_16x16x32_bf16 v[56:59], v[150:153], v[228:231], v[56:59]
	v_mfma_f32_16x16x32_bf16 v[60:63], v[154:157], v[224:227], v[60:63]
	v_mfma_f32_16x16x32_bf16 v[60:63], v[158:161], v[228:231], v[60:63]
	v_mfma_f32_16x16x32_bf16 v[44:47], v[146:149], v[232:235], v[44:47]
	v_mfma_f32_16x16x32_bf16 v[44:47], v[150:153], v[236:239], v[44:47]
	v_mfma_f32_16x16x32_bf16 v[40:43], v[154:157], v[232:235], v[40:43]
	v_mfma_f32_16x16x32_bf16 v[40:43], v[158:161], v[236:239], v[40:43]
	v_mfma_f32_16x16x32_bf16 v[28:31], v[146:149], v[240:243], v[28:31]
	v_mfma_f32_16x16x32_bf16 v[28:31], v[150:153], v[244:247], v[28:31]
	v_mfma_f32_16x16x32_bf16 v[24:27], v[154:157], v[240:243], v[24:27]
	v_mfma_f32_16x16x32_bf16 v[24:27], v[158:161], v[244:247], v[24:27]
	v_mfma_f32_16x16x32_bf16 v[12:15], v[146:149], v[248:251], v[12:15]
	v_mfma_f32_16x16x32_bf16 v[12:15], v[150:153], v[210:213], v[12:15]
	v_mfma_f32_16x16x32_bf16 v[8:11], v[154:157], v[248:251], v[8:11]
	v_mfma_f32_16x16x32_bf16 v[8:11], v[158:161], v[210:213], v[8:11]
	s_setprio 0
	s_setprio 1
	v_mfma_f32_16x16x32_bf16 v[52:55], v[162:165], v[224:227], v[52:55]
	v_mfma_f32_16x16x32_bf16 v[52:55], v[166:169], v[228:231], v[52:55]
	v_mfma_f32_16x16x32_bf16 v[48:51], v[170:173], v[224:227], v[48:51]
	v_mfma_f32_16x16x32_bf16 v[48:51], v[174:177], v[228:231], v[48:51]
	v_mfma_f32_16x16x32_bf16 v[36:39], v[162:165], v[232:235], v[36:39]
	v_mfma_f32_16x16x32_bf16 v[36:39], v[166:169], v[236:239], v[36:39]
	v_mfma_f32_16x16x32_bf16 v[32:35], v[170:173], v[232:235], v[32:35]
	v_mfma_f32_16x16x32_bf16 v[32:35], v[174:177], v[236:239], v[32:35]
	v_mfma_f32_16x16x32_bf16 v[20:23], v[162:165], v[240:243], v[20:23]
	v_mfma_f32_16x16x32_bf16 v[20:23], v[166:169], v[244:247], v[20:23]
	v_mfma_f32_16x16x32_bf16 v[16:19], v[170:173], v[240:243], v[16:19]
	v_mfma_f32_16x16x32_bf16 v[16:19], v[174:177], v[244:247], v[16:19]
	v_mfma_f32_16x16x32_bf16 v[4:7], v[162:165], v[248:251], v[4:7]
	v_mfma_f32_16x16x32_bf16 v[4:7], v[166:169], v[210:213], v[4:7]
	v_mfma_f32_16x16x32_bf16 v[0:3], v[170:173], v[248:251], v[0:3]
	v_mfma_f32_16x16x32_bf16 v[0:3], v[174:177], v[210:213], v[0:3]
	s_setprio 0
	s_barrier
	s_add_u32 s80, s80, 0x100
	s_addc_u32 s81, s81, 0
	s_add_u32 s59, s59, 0x100
	s_addc_u32 s61, s61, 0
	s_cmp_ge_i32 s63, s57
	s_mov_b32 s82, s63
	s_cbranch_scc0 .LBB0_1077
	s_mov_b64 s[4:5], 0x80

; #define PG8_STAGE(bufoff, gbase, voff) do { _Pragma("unroll") for (int _i = 0; _i < 2; ++_i) \
;         __builtin_amdgcn_global_load_lds((const unsigned*)((const char*)(gbase) + (voff)[_i]), (PG8_LAS unsigned*)(lds + (bufoff) + ldsw + _i * 8192), 16, 0, 0); } while (0)
; #define PG8_LDA(dst, b, h) do { _Pragma("unroll") for (int m = 0; m < 4; ++m) _Pragma("unroll") for (int k = 0; k < 2; ++k) dst[m][k] = *(const PG8_LAS bf16x8*)(lds + PG8_SA(b, h) + aoff + m * 2048 + k * 1024); } while (0)
; #define PG8_LDB(dst, b, h) do { _Pragma("unroll") for (int n = 0; n < 2; ++n) _Pragma("unroll") for (int k = 0; k < 2; ++k) dst[n][k] = *(const PG8_LAS bf16x8*)(lds + PG8_SB(b, h) + boff + n * 2048 + k * 1024); } while (0)
; #define PG8_MMA(ai, bj, At, Bt) do { __builtin_amdgcn_s_setprio(1); _Pragma("unroll") for (int m = 0; m < 4; ++m) _Pragma("unroll") for (int n = 0; n < 2; ++n) _Pragma("unroll") for (int k = 0; k < 2; ++k) \
;         acc[ai][bj][m][n] = __builtin_amdgcn_mfma_f32_16x16x32_bf16(Bt[n][k], At[m][k], acc[ai][bj][m][n], 0, 0, 0); __builtin_amdgcn_s_setprio(0); } while (0)
; #define PG8_WAIT_V(n) asm volatile("s_waitcnt vmcnt(" #n ")" ::: "memory")
; #define PG8_WAIT_L(n) asm volatile("s_waitcnt lgkmcnt(" #n ")" ::: "memory")
; template <class Epi, class Sched, bool ALIGN_EPI = true, bool SP2 = true>
; __device__ __forceinline__ void gemm_phase(PG8_LAS unsigned char* lds, const Gemm g, const Sched& S, const Epi& E, const int tid) {
;     ...
;             const bool last = (t == nt - 2);
;             const char* a1 = cA + (size_t)(t + 1) * kstep;
;             const char* a2 = last ? nA : cA + (size_t)(t + 2) * kstep; const char* b2 = last ? nB : cB + (size_t)(t + 2) * kstep;
;             const char* a3 = a2 + kstep; const char* b3 = b2 + kstep;
;             if (last && has_next) S.a_ready(nxt);
;             if constexpr (SP2) {
;             PG8_LDB(B0, 0, 0); PG8_LDB(B1, 0, 1); PG8_SCHED; PG8_LDA(At, 0, 0); PG8_STAGE(PG8_SA(1, 1), a1 + hstepA, voffA);
;             PG8_WAIT_V(8); PG8_WAIT_L(0); PG8_BAR; PG8_MMA(0, 0, At, B0); PG8_MMA(0, 1, At, B1); PG8_BAR; PG8_SCHED;
;             PG8_LDA(At, 0, 1); PG8_STAGE(PG8_SB(0, 0), b2, voffB); PG8_STAGE(PG8_SB(0, 1), b2 + hstepB, voffB); PG8_STAGE(PG8_SA(0, 0), a2, voffA);
;             PG8_WAIT_V(8); PG8_WAIT_L(0); PG8_BAR; PG8_MMA(1, 0, At, B0); PG8_MMA(1, 1, At, B1); PG8_BAR; PG8_SCHED;
.LBB0_1319:
	s_add_u32 s28, s62, 0xfff80080
	s_addc_u32 s29, s63, -1
	s_add_i32 s30, 0, 0x10000
	s_cmp_eq_u32 s52, 28
	s_cselect_b32 s67, s24, s29
	s_cselect_b32 s66, s25, s28
	v_add_u32_e32 v145, s30, v142
	s_cselect_b32 s65, s26, s51
	s_cselect_b32 s64, s27, s49
	s_add_i32 s31, 0, 0x14000
	ds_read_b128 v[146:149], v145
	ds_read_b128 v[150:153], v145 offset:1024
	ds_read_b128 v[154:157], v145 offset:2048
	ds_read_b128 v[158:161], v145 offset:3072
	v_add_u32_e32 v145, s31, v142
	ds_read_b128 v[162:165], v145
	ds_read_b128 v[166:169], v145 offset:1024
	ds_read_b128 v[170:173], v145 offset:2048
	ds_read_b128 v[174:177], v145 offset:3072
	s_add_i32 m0, s22, 0xc000
	ds_read_b128 v[178:181], v144
	ds_read_b128 v[182:185], v144 offset:1024
	ds_read_b128 v[186:189], v144 offset:2048
	ds_read_b128 v[190:193], v144 offset:3072
	ds_read_b128 v[194:197], v144 offset:4096
	ds_read_b128 v[200:203], v144 offset:5120
	ds_read_b128 v[206:209], v144 offset:6144
	ds_read_b128 v[210:213], v144 offset:7168
	global_load_lds_dwordx4 v138, s[62:63]
	s_add_i32 m0, s22, 0xe000
	s_nop 0
	global_load_lds_dwordx4 v140, s[62:63]
	s_waitcnt vmcnt(8)
	s_waitcnt lgkmcnt(0)
	s_barrier
	s_setprio 1
	s_waitcnt lgkmcnt(0)
	v_mfma_f32_16x16x32_bf16 v[126:129], v[146:149], v[178:181], v[126:129]
	v_mfma_f32_16x16x32_bf16 v[126:129], v[150:153], v[182:185], v[126:129]
	ds_read_b128 v[218:221], v144 offset:16384
	v_mfma_f32_16x16x32_bf16 v[118:121], v[154:157], v[178:181], v[118:121]
	v_mfma_f32_16x16x32_bf16 v[118:121], v[158:161], v[182:185], v[118:121]
	v_mfma_f32_16x16x32_bf16 v[110:113], v[146:149], v[186:189], v[110:113]
	v_mfma_f32_16x16x32_bf16 v[110:113], v[150:153], v[190:193], v[110:113]
	ds_read_b128 v[222:225], v144 offset:17408
	v_mfma_f32_16x16x32_bf16 v[102:105], v[154:157], v[186:189], v[102:105]
	v_mfma_f32_16x16x32_bf16 v[102:105], v[158:161], v[190:193], v[102:105]
	v_mfma_f32_16x16x32_bf16 v[92:95], v[146:149], v[194:197], v[92:95]
	v_mfma_f32_16x16x32_bf16 v[92:95], v[150:153], v[200:203], v[92:95]
	ds_read_b128 v[226:229], v144 offset:18432
	v_mfma_f32_16x16x32_bf16 v[84:87], v[154:157], v[194:197], v[84:87]
	v_mfma_f32_16x16x32_bf16 v[84:87], v[158:161], v[200:203], v[84:87]
	v_mfma_f32_16x16x32_bf16 v[76:79], v[146:149], v[206:209], v[76:79]
	v_mfma_f32_16x16x32_bf16 v[76:79], v[150:153], v[210:213], v[76:79]
	ds_read_b128 v[230:233], v144 offset:19456
	v_mfma_f32_16x16x32_bf16 v[68:71], v[154:157], v[206:209], v[68:71]
	v_mfma_f32_16x16x32_bf16 v[68:71], v[158:161], v[210:213], v[68:71]
	s_setprio 0
	s_setprio 1
	v_mfma_f32_16x16x32_bf16 v[122:125], v[162:165], v[178:181], v[122:125]
	v_mfma_f32_16x16x32_bf16 v[122:125], v[166:169], v[182:185], v[122:125]
	ds_read_b128 v[234:237], v144 offset:20480
	v_mfma_f32_16x16x32_bf16 v[114:117], v[170:173], v[178:181], v[114:117]
	v_mfma_f32_16x16x32_bf16 v[114:117], v[174:177], v[182:185], v[114:117]
	v_mfma_f32_16x16x32_bf16 v[106:109], v[162:165], v[186:189], v[106:109]
	v_mfma_f32_16x16x32_bf16 v[106:109], v[166:169], v[190:193], v[106:109]
	ds_read_b128 v[238:241], v144 offset:21504
	v_mfma_f32_16x16x32_bf16 v[98:101], v[170:173], v[186:189], v[98:101]
	v_mfma_f32_16x16x32_bf16 v[98:101], v[174:177], v[190:193], v[98:101]
	v_mfma_f32_16x16x32_bf16 v[88:91], v[162:165], v[194:197], v[88:91]
	v_mfma_f32_16x16x32_bf16 v[88:91], v[166:169], v[200:203], v[88:91]
	ds_read_b128 v[242:245], v144 offset:22528
	v_mfma_f32_16x16x32_bf16 v[80:83], v[170:173], v[194:197], v[80:83]
	v_mfma_f32_16x16x32_bf16 v[80:83], v[174:177], v[200:203], v[80:83]
	v_mfma_f32_16x16x32_bf16 v[72:75], v[162:165], v[206:209], v[72:75]
	v_mfma_f32_16x16x32_bf16 v[72:75], v[166:169], v[210:213], v[72:75]
	ds_read_b128 v[246:249], v144 offset:23552
	v_mfma_f32_16x16x32_bf16 v[64:67], v[170:173], v[206:209], v[64:67]
	v_mfma_f32_16x16x32_bf16 v[64:67], v[174:177], v[210:213], v[64:67]
	s_setprio 0
	s_barrier
	s_add_i32 s28, s30, s21
	s_mov_b32 m0, s28
	s_nop 0
	global_load_lds_dwordx4 v134, s[64:65]
	s_add_i32 m0, s28, 0x2000
	s_add_u32 s28, s64, 0x80000
	s_addc_u32 s29, s65, 0
	s_add_i32 s30, s31, s21
	global_load_lds_dwordx4 v130, s[64:65]
	s_mov_b32 m0, s30
	s_nop 0
	global_load_lds_dwordx4 v134, s[28:29]
	s_add_i32 m0, s30, 0x2000
	s_nop 0
	global_load_lds_dwordx4 v130, s[28:29]
	s_mov_b32 m0, s22
	s_nop 0
	global_load_lds_dwordx4 v136, s[66:67]
	s_mov_b32 m0, s23
	s_nop 0
	global_load_lds_dwordx4 v132, s[66:67]
	s_waitcnt vmcnt(6)
	s_waitcnt lgkmcnt(0)
	s_barrier
	s_setprio 1
	s_waitcnt lgkmcnt(0)
	v_mfma_f32_16x16x32_bf16 v[60:63], v[146:149], v[218:221], v[60:63]
	v_mfma_f32_16x16x32_bf16 v[60:63], v[150:153], v[222:225], v[60:63]
	v_mfma_f32_16x16x32_bf16 v[52:55], v[154:157], v[218:221], v[52:55]
	v_mfma_f32_16x16x32_bf16 v[52:55], v[158:161], v[222:225], v[52:55]
	v_mfma_f32_16x16x32_bf16 v[44:47], v[146:149], v[226:229], v[44:47]
	v_mfma_f32_16x16x32_bf16 v[44:47], v[150:153], v[230:233], v[44:47]
	v_mfma_f32_16x16x32_bf16 v[36:39], v[154:157], v[226:229], v[36:39]
	v_mfma_f32_16x16x32_bf16 v[36:39], v[158:161], v[230:233], v[36:39]
	v_mfma_f32_16x16x32_bf16 v[28:31], v[146:149], v[234:237], v[28:31]
	v_mfma_f32_16x16x32_bf16 v[28:31], v[150:153], v[238:241], v[28:31]
	v_mfma_f32_16x16x32_bf16 v[20:23], v[154:157], v[234:237], v[20:23]
	v_mfma_f32_16x16x32_bf16 v[20:23], v[158:161], v[238:241], v[20:23]
	v_mfma_f32_16x16x32_bf16 v[12:15], v[146:149], v[242:245], v[12:15]
	v_mfma_f32_16x16x32_bf16 v[12:15], v[150:153], v[246:249], v[12:15]
	v_mfma_f32_16x16x32_bf16 v[4:7], v[154:157], v[242:245], v[4:7]
	v_mfma_f32_16x16x32_bf16 v[4:7], v[158:161], v[246:249], v[4:7]
	s_setprio 0
	s_setprio 1
	v_mfma_f32_16x16x32_bf16 v[56:59], v[162:165], v[218:221], v[56:59]
	v_mfma_f32_16x16x32_bf16 v[56:59], v[166:169], v[222:225], v[56:59]
	v_mfma_f32_16x16x32_bf16 v[48:51], v[170:173], v[218:221], v[48:51]
	v_mfma_f32_16x16x32_bf16 v[48:51], v[174:177], v[222:225], v[48:51]
	v_mfma_f32_16x16x32_bf16 v[40:43], v[162:165], v[226:229], v[40:43]
	v_mfma_f32_16x16x32_bf16 v[40:43], v[166:169], v[230:233], v[40:43]
	v_mfma_f32_16x16x32_bf16 v[32:35], v[170:173], v[226:229], v[32:35]
	v_mfma_f32_16x16x32_bf16 v[32:35], v[174:177], v[230:233], v[32:35]
	v_mfma_f32_16x16x32_bf16 v[24:27], v[162:165], v[234:237], v[24:27]
	v_mfma_f32_16x16x32_bf16 v[24:27], v[166:169], v[238:241], v[24:27]
	v_mfma_f32_16x16x32_bf16 v[16:19], v[170:173], v[234:237], v[16:19]
	v_mfma_f32_16x16x32_bf16 v[16:19], v[174:177], v[238:241], v[16:19]
	v_mfma_f32_16x16x32_bf16 v[8:11], v[162:165], v[242:245], v[8:11]
	v_mfma_f32_16x16x32_bf16 v[8:11], v[166:169], v[246:249], v[8:11]
	v_mfma_f32_16x16x32_bf16 v[0:3], v[170:173], v[242:245], v[0:3]
	v_mfma_f32_16x16x32_bf16 v[0:3], v[174:177], v[246:249], v[0:3]
	s_setprio 0
	s_barrier
; #define PG8_STAGE(bufoff, gbase, voff) do { _Pragma("unroll") for (int _i = 0; _i < 2; ++_i) \
;         __builtin_amdgcn_global_load_lds((const unsigned*)((const char*)(gbase) + (voff)[_i]), (PG8_LAS unsigned*)(lds + (bufoff) + ldsw + _i * 8192), 16, 0, 0); } while (0)
; #define PG8_LDA(dst, b, h) do { _Pragma("unroll") for (int m = 0; m < 4; ++m) _Pragma("unroll") for (int k = 0; k < 2; ++k) dst[m][k] = *(const PG8_LAS bf16x8*)(lds + PG8_SA(b, h) + aoff + m * 2048 + k * 1024); } while (0)
; #define PG8_LDB(dst, b, h) do { _Pragma("unroll") for (int n = 0; n < 2; ++n) _Pragma("unroll") for (int k = 0; k < 2; ++k) dst[n][k] = *(const PG8_LAS bf16x8*)(lds + PG8_SB(b, h) + boff + n * 2048 + k * 1024); } while (0)
; #define PG8_MMA(ai, bj, At, Bt) do { __builtin_amdgcn_s_setprio(1); _Pragma("unroll") for (int m = 0; m < 4; ++m) _Pragma("unroll") for (int n = 0; n < 2; ++n) _Pragma("unroll") for (int k = 0; k < 2; ++k) \
;         acc[ai][bj][m][n] = __builtin_amdgcn_mfma_f32_16x16x32_bf16(Bt[n][k], At[m][k], acc[ai][bj][m][n], 0, 0, 0); __builtin_amdgcn_s_setprio(0); } while (0)
; #define PG8_WAIT_V(n) asm volatile("s_waitcnt vmcnt(" #n ")" ::: "memory")
; #define PG8_WAIT_L(n) asm volatile("s_waitcnt lgkmcnt(" #n ")" ::: "memory")
; #define PG8_BAR __builtin_amdgcn_s_barrier()
; template <class Epi, class Sched, bool ALIGN_EPI = true, bool SP2 = true>
; __device__ __forceinline__ void gemm_phase(PG8_LAS unsigned char* lds, const Gemm g, const Sched& S, const Epi& E, const int tid) {
;     ...
;         for (int t = 0; t < nt; t += 2) {
;             const bool last = (t == nt - 2);
;             const char* a1 = cA + (size_t)(t + 1) * kstep;
;             const char* a2 = last ? nA : cA + (size_t)(t + 2) * kstep; const char* b2 = last ? nB : cB + (size_t)(t + 2) * kstep;
;             const char* a3 = a2 + kstep; const char* b3 = b2 + kstep;
;     ...
;             PG8_LDB(B0, 1, 0); PG8_LDB(B1, 1, 1); PG8_SCHED; PG8_LDA(At, 1, 0); PG8_STAGE(PG8_SA(0, 1), a2 + hstepA, voffA);
;             PG8_WAIT_V(8); PG8_WAIT_L(0); PG8_BAR; PG8_MMA(0, 0, At, B0); PG8_MMA(0, 1, At, B1); PG8_BAR; PG8_SCHED;
;             PG8_LDA(At, 1, 1); PG8_STAGE(PG8_SB(1, 0), b3, voffB); PG8_STAGE(PG8_SB(1, 1), b3 + hstepB, voffB); PG8_STAGE(PG8_SA(1, 0), a3, voffA);
;             PG8_WAIT_V(8); PG8_WAIT_L(0); PG8_BAR; PG8_MMA(1, 0, At, B0); PG8_MMA(1, 1, At, B1); PG8_BAR; PG8_SCHED;
	s_add_i32 s30, 0, 0x18000
	v_add_u32_e32 v145, s30, v142
	s_add_i32 s31, 0, 0x1c000
	ds_read_b128 v[146:149], v145
	ds_read_b128 v[150:153], v145 offset:1024
	ds_read_b128 v[154:157], v145 offset:2048
	ds_read_b128 v[158:161], v145 offset:3072
	v_add_u32_e32 v145, s31, v142
	ds_read_b128 v[162:165], v145
	ds_read_b128 v[166:169], v145 offset:1024
	ds_read_b128 v[170:173], v145 offset:2048
	ds_read_b128 v[174:177], v145 offset:3072
	s_add_u32 s28, s66, 0x80000
	s_addc_u32 s29, s67, 0
	s_mov_b32 m0, s61
	ds_read_b128 v[178:181], v144 offset:32768
	ds_read_b128 v[182:185], v144 offset:33792
	ds_read_b128 v[186:189], v144 offset:34816
	ds_read_b128 v[190:193], v144 offset:35840
	ds_read_b128 v[194:197], v144 offset:36864
	ds_read_b128 v[200:203], v144 offset:37888
	ds_read_b128 v[206:209], v144 offset:38912
	ds_read_b128 v[210:213], v144 offset:39936
	global_load_lds_dwordx4 v136, s[28:29]
	s_mov_b32 m0, s70
	s_nop 0
	global_load_lds_dwordx4 v132, s[28:29]
	s_waitcnt vmcnt(8)
	s_waitcnt lgkmcnt(0)
	s_barrier
	s_setprio 1
	s_waitcnt lgkmcnt(0)
	v_mfma_f32_16x16x32_bf16 v[126:129], v[146:149], v[178:181], v[126:129]
	v_mfma_f32_16x16x32_bf16 v[126:129], v[150:153], v[182:185], v[126:129]
	ds_read_b128 v[218:221], v144 offset:49152
	v_mfma_f32_16x16x32_bf16 v[118:121], v[154:157], v[178:181], v[118:121]
	v_mfma_f32_16x16x32_bf16 v[118:121], v[158:161], v[182:185], v[118:121]
	v_mfma_f32_16x16x32_bf16 v[110:113], v[146:149], v[186:189], v[110:113]
	v_mfma_f32_16x16x32_bf16 v[110:113], v[150:153], v[190:193], v[110:113]
	ds_read_b128 v[222:225], v144 offset:50176
	v_mfma_f32_16x16x32_bf16 v[102:105], v[154:157], v[186:189], v[102:105]
	v_mfma_f32_16x16x32_bf16 v[102:105], v[158:161], v[190:193], v[102:105]
	v_mfma_f32_16x16x32_bf16 v[92:95], v[146:149], v[194:197], v[92:95]
	v_mfma_f32_16x16x32_bf16 v[92:95], v[150:153], v[200:203], v[92:95]
	ds_read_b128 v[226:229], v144 offset:51200
	v_mfma_f32_16x16x32_bf16 v[84:87], v[154:157], v[194:197], v[84:87]
	v_mfma_f32_16x16x32_bf16 v[84:87], v[158:161], v[200:203], v[84:87]
	v_mfma_f32_16x16x32_bf16 v[76:79], v[146:149], v[206:209], v[76:79]
	v_mfma_f32_16x16x32_bf16 v[76:79], v[150:153], v[210:213], v[76:79]
	ds_read_b128 v[230:233], v144 offset:52224
	v_mfma_f32_16x16x32_bf16 v[68:71], v[154:157], v[206:209], v[68:71]
	v_mfma_f32_16x16x32_bf16 v[68:71], v[158:161], v[210:213], v[68:71]
	s_setprio 0
	s_setprio 1
	v_mfma_f32_16x16x32_bf16 v[122:125], v[162:165], v[178:181], v[122:125]
	v_mfma_f32_16x16x32_bf16 v[122:125], v[166:169], v[182:185], v[122:125]
	ds_read_b128 v[234:237], v144 offset:53248
	v_mfma_f32_16x16x32_bf16 v[114:117], v[170:173], v[178:181], v[114:117]
	v_mfma_f32_16x16x32_bf16 v[114:117], v[174:177], v[182:185], v[114:117]
	v_mfma_f32_16x16x32_bf16 v[106:109], v[162:165], v[186:189], v[106:109]
	v_mfma_f32_16x16x32_bf16 v[106:109], v[166:169], v[190:193], v[106:109]
	ds_read_b128 v[238:241], v144 offset:54272
	v_mfma_f32_16x16x32_bf16 v[98:101], v[170:173], v[186:189], v[98:101]
	v_mfma_f32_16x16x32_bf16 v[98:101], v[174:177], v[190:193], v[98:101]
	v_mfma_f32_16x16x32_bf16 v[88:91], v[162:165], v[194:197], v[88:91]
	v_mfma_f32_16x16x32_bf16 v[88:91], v[166:169], v[200:203], v[88:91]
	ds_read_b128 v[242:245], v144 offset:55296
	v_mfma_f32_16x16x32_bf16 v[80:83], v[170:173], v[194:197], v[80:83]
	v_mfma_f32_16x16x32_bf16 v[80:83], v[174:177], v[200:203], v[80:83]
	v_mfma_f32_16x16x32_bf16 v[72:75], v[162:165], v[206:209], v[72:75]
	v_mfma_f32_16x16x32_bf16 v[72:75], v[166:169], v[210:213], v[72:75]
	ds_read_b128 v[246:249], v144 offset:56320
	v_mfma_f32_16x16x32_bf16 v[64:67], v[170:173], v[206:209], v[64:67]
	v_mfma_f32_16x16x32_bf16 v[64:67], v[174:177], v[210:213], v[64:67]
	s_setprio 0
	s_barrier
	s_add_i32 s28, s30, s21
	s_add_u32 s4, s64, 0x80
	s_addc_u32 s5, s65, 0
	s_mov_b32 m0, s28
	s_nop 0
	global_load_lds_dwordx4 v134, s[4:5]
	s_add_i32 m0, s28, 0x2000
	s_add_u32 s28, s64, 0x80080
	s_addc_u32 s29, s65, 0
	s_add_i32 s30, s31, s21
	global_load_lds_dwordx4 v130, s[4:5]
	s_mov_b32 m0, s30
	s_nop 0
	global_load_lds_dwordx4 v134, s[28:29]
	s_add_i32 m0, s30, 0x2000
	s_nop 0
	global_load_lds_dwordx4 v130, s[28:29]
	s_add_u32 s4, s66, 0x80
	s_addc_u32 s5, s67, 0
	s_mov_b32 m0, s71
	s_nop 0
	global_load_lds_dwordx4 v136, s[4:5]
	s_mov_b32 m0, s72
	s_nop 0
	global_load_lds_dwordx4 v132, s[4:5]
	s_waitcnt vmcnt(6)
	s_waitcnt lgkmcnt(0)
	s_barrier
	s_setprio 1
	s_waitcnt lgkmcnt(0)
	v_mfma_f32_16x16x32_bf16 v[60:63], v[146:149], v[218:221], v[60:63]
	v_mfma_f32_16x16x32_bf16 v[60:63], v[150:153], v[222:225], v[60:63]
	v_mfma_f32_16x16x32_bf16 v[52:55], v[154:157], v[218:221], v[52:55]
	v_mfma_f32_16x16x32_bf16 v[52:55], v[158:161], v[222:225], v[52:55]
	v_mfma_f32_16x16x32_bf16 v[44:47], v[146:149], v[226:229], v[44:47]
	v_mfma_f32_16x16x32_bf16 v[44:47], v[150:153], v[230:233], v[44:47]
	v_mfma_f32_16x16x32_bf16 v[36:39], v[154:157], v[226:229], v[36:39]
	v_mfma_f32_16x16x32_bf16 v[36:39], v[158:161], v[230:233], v[36:39]
	v_mfma_f32_16x16x32_bf16 v[28:31], v[146:149], v[234:237], v[28:31]
	v_mfma_f32_16x16x32_bf16 v[28:31], v[150:153], v[238:241], v[28:31]
	v_mfma_f32_16x16x32_bf16 v[20:23], v[154:157], v[234:237], v[20:23]
	v_mfma_f32_16x16x32_bf16 v[20:23], v[158:161], v[238:241], v[20:23]
	v_mfma_f32_16x16x32_bf16 v[12:15], v[146:149], v[242:245], v[12:15]
	v_mfma_f32_16x16x32_bf16 v[12:15], v[150:153], v[246:249], v[12:15]
	v_mfma_f32_16x16x32_bf16 v[4:7], v[154:157], v[242:245], v[4:7]
	v_mfma_f32_16x16x32_bf16 v[4:7], v[158:161], v[246:249], v[4:7]
	s_setprio 0
	s_setprio 1
	v_mfma_f32_16x16x32_bf16 v[56:59], v[162:165], v[218:221], v[56:59]
	v_mfma_f32_16x16x32_bf16 v[56:59], v[166:169], v[222:225], v[56:59]
	v_mfma_f32_16x16x32_bf16 v[48:51], v[170:173], v[218:221], v[48:51]
	v_mfma_f32_16x16x32_bf16 v[48:51], v[174:177], v[222:225], v[48:51]
	v_mfma_f32_16x16x32_bf16 v[40:43], v[162:165], v[226:229], v[40:43]
	v_mfma_f32_16x16x32_bf16 v[40:43], v[166:169], v[230:233], v[40:43]
	v_mfma_f32_16x16x32_bf16 v[32:35], v[170:173], v[226:229], v[32:35]
	v_mfma_f32_16x16x32_bf16 v[32:35], v[174:177], v[230:233], v[32:35]
	v_mfma_f32_16x16x32_bf16 v[24:27], v[162:165], v[234:237], v[24:27]
	v_mfma_f32_16x16x32_bf16 v[24:27], v[166:169], v[238:241], v[24:27]
	v_mfma_f32_16x16x32_bf16 v[16:19], v[170:173], v[234:237], v[16:19]
	v_mfma_f32_16x16x32_bf16 v[16:19], v[174:177], v[238:241], v[16:19]
	v_mfma_f32_16x16x32_bf16 v[8:11], v[162:165], v[242:245], v[8:11]
	v_mfma_f32_16x16x32_bf16 v[8:11], v[166:169], v[246:249], v[8:11]
	v_mfma_f32_16x16x32_bf16 v[0:3], v[170:173], v[242:245], v[0:3]
	v_mfma_f32_16x16x32_bf16 v[0:3], v[174:177], v[246:249], v[0:3]
	s_setprio 0
	s_barrier
	s_add_i32 s52, s52, 2
	s_add_u32 s62, s62, 0x100
	s_addc_u32 s63, s63, 0
	s_add_u32 s49, s49, 0x100
	s_addc_u32 s51, s51, 0
	s_cmp_gt_u32 s52, 29
	s_cbranch_scc0 .LBB0_1319
	v_mov_b32_e32 v218, 0x2a00
	v_mov_b32_e32 v219, 0xf149f2ca
	v_mov_b32_e32 v220, 0xe00
	s_mov_b64 s[4:5], 0x80
	s_and_b64 vcc, exec, s[46:47]
	s_cbranch_vccz .LBB0_1322
	s_barrier
